# EpiResid residual loads marked nt (each line is now read exactly once)
# speedup vs baseline: 1.0036x; 1.0036x over previous
;     __device__ __forceinline__ void operator()(const f32x4 (&acc)[2][2][4][2], const pg8::Unit& u, int wr, int wc, int fr, int fq) const {
;         const int row0 = u.pm * 256 + wr * 64 + fr; const float* gp = gate + (size_t)(u.pm >> 5) * NMOD;
; #pragma unroll
;         for (int bj = 0; bj < 2; ++bj) {
;             const int col = u.pn * 256 + bj * 128 + wc * 32 + 8 * fq;
;             const f32x4 g0 = *(const f32x4*)(gp + col) * coef, g1 = *(const f32x4*)(gp + col + 4) * coef;
; #pragma unroll
;             for (int ai = 0; ai < 2; ++ai)
; #pragma unroll
;                 for (int m = 0; m < 4; ++m) {
;                     const size_t off = (size_t)(row0 + ai * 128 + m * 16) * DM + col;
;                     const f32x4 x0 = *(const f32x4*)(base + off), x1 = *(const f32x4*)(base + off + 4);
;                     *(f32x4*)(out + off) = x0 + g0 * acc[ai][bj][m][0]; *(f32x4*)(out + off + 4) = x1 + g1 * acc[ai][bj][m][1];
;                     if (m & 1) asm volatile("" ::: "memory");
;                 }
.LBB0_235:
	v_and_b32_e32 v243, 8, v160
	v_sub_u32_e32 v240, v160, v243
	v_lshrrev_b32_e32 v243, 1, v243
	v_add_u32_e32 v241, v162, v243
	v_lshl_add_u32 v240, s70, 8, v240
	v_lshl_add_u32 v241, s71, 8, v241
	v_lshlrev_b32_e32 v240, 10, v240
	v_add_lshl_u32 v240, v240, v241, 2
	v_lshlrev_b32_e32 v241, 2, v241
	v_add_u32_e32 v242, 0x8000, v240
	s_ashr_i32 s98, s70, 5
	s_mul_i32 s98, s98, 0x9000
	s_add_u32 s98, s44, s98
	s_addc_u32 s99, s45, 0
	global_load_dwordx4 v[144:147], v241, s[98:99]
	s_add_u32 s100, s36, 0x0
	s_addc_u32 s101, s37, 0
	global_load_dwordx4 v[172:175], v240, s[100:101] nt
	global_load_dwordx4 v[176:179], v242, s[100:101] nt
	s_add_u32 s100, s36, 0x10000
	s_addc_u32 s101, s37, 0
	global_load_dwordx4 v[180:183], v240, s[100:101] nt
	global_load_dwordx4 v[184:187], v242, s[100:101] nt
	s_add_u32 s100, s36, 0x20000
	s_addc_u32 s101, s37, 0
	global_load_dwordx4 v[188:191], v240, s[100:101] nt
	global_load_dwordx4 v[192:195], v242, s[100:101] nt
	s_add_u32 s100, s36, 0x30000
	s_addc_u32 s101, s37, 0
	global_load_dwordx4 v[196:199], v240, s[100:101] nt
	global_load_dwordx4 v[200:203], v242, s[100:101] nt
	s_add_u32 s100, s36, 0x80000
	s_addc_u32 s101, s37, 0
	global_load_dwordx4 v[208:211], v240, s[100:101] nt
	global_load_dwordx4 v[212:215], v242, s[100:101] nt
	s_add_u32 s100, s36, 0x90000
	s_addc_u32 s101, s37, 0
	global_load_dwordx4 v[216:219], v240, s[100:101] nt
	global_load_dwordx4 v[220:223], v242, s[100:101] nt
	s_add_u32 s100, s36, 0xa0000
	s_addc_u32 s101, s37, 0
	global_load_dwordx4 v[224:227], v240, s[100:101] nt
	global_load_dwordx4 v[228:231], v242, s[100:101] nt
	s_add_u32 s100, s36, 0xb0000
	s_addc_u32 s101, s37, 0
	global_load_dwordx4 v[232:235], v240, s[100:101] nt
	global_load_dwordx4 v[236:239], v242, s[100:101] nt
	v_mov_b32_dpp v148, v120 row_ror:8 row_mask:0xf bank_mask:0xf
	v_mov_b32_dpp v149, v121 row_ror:8 row_mask:0xf bank_mask:0xf
	v_mov_b32_dpp v150, v122 row_ror:8 row_mask:0xf bank_mask:0xf
	v_mov_b32_dpp v151, v123 row_ror:8 row_mask:0xf bank_mask:0xf
	v_mov_b32_dpp v120, v124 row_ror:8 row_mask:0xf bank_mask:0x3
	v_mov_b32_dpp v121, v125 row_ror:8 row_mask:0xf bank_mask:0x3
	v_mov_b32_dpp v122, v126 row_ror:8 row_mask:0xf bank_mask:0x3
	v_mov_b32_dpp v123, v127 row_ror:8 row_mask:0xf bank_mask:0x3
	v_mov_b32_dpp v124, v148 quad_perm:[0,1,2,3] row_mask:0xf bank_mask:0xc
	v_mov_b32_dpp v125, v149 quad_perm:[0,1,2,3] row_mask:0xf bank_mask:0xc
	v_mov_b32_dpp v126, v150 quad_perm:[0,1,2,3] row_mask:0xf bank_mask:0xc
	v_mov_b32_dpp v127, v151 quad_perm:[0,1,2,3] row_mask:0xf bank_mask:0xc
	s_waitcnt vmcnt(16)
	v_pk_mul_f32 v[144:145], v[144:145], 0.5 op_sel_hi:[1,0]
	v_pk_mul_f32 v[146:147], v[146:147], 0.5 op_sel_hi:[1,0]
	s_waitcnt vmcnt(14)
	v_pk_fma_f32 v[124:125], v[124:125], v[144:145], v[172:173]
	v_pk_fma_f32 v[126:127], v[126:127], v[146:147], v[174:175]
	v_pk_fma_f32 v[120:121], v[120:121], v[144:145], v[176:177]
	v_pk_fma_f32 v[122:123], v[122:123], v[146:147], v[178:179]
	s_add_u32 s98, s90, 0x0
	s_addc_u32 s99, s91, 0
	global_store_dwordx4 v240, v[124:127], s[98:99]
	global_store_dwordx4 v242, v[120:123], s[98:99]
	s_add_u32 s100, s36, 0x0
	s_addc_u32 s101, s37, 0
	global_load_dwordx4 v[172:175], v240, s[100:101] offset:512 nt
	global_load_dwordx4 v[176:179], v242, s[100:101] offset:512 nt
	s_ashr_i32 s98, s70, 5
	s_mul_i32 s98, s98, 0x9000
	s_add_u32 s98, s44, s98
	s_addc_u32 s99, s45, 0
	global_load_dwordx4 v[120:123], v241, s[98:99] offset:512
	v_mov_b32_dpp v148, v112 row_ror:8 row_mask:0xf bank_mask:0xf
	v_mov_b32_dpp v149, v113 row_ror:8 row_mask:0xf bank_mask:0xf
	v_mov_b32_dpp v150, v114 row_ror:8 row_mask:0xf bank_mask:0xf
	v_mov_b32_dpp v151, v115 row_ror:8 row_mask:0xf bank_mask:0xf
	v_mov_b32_dpp v112, v116 row_ror:8 row_mask:0xf bank_mask:0x3
	v_mov_b32_dpp v113, v117 row_ror:8 row_mask:0xf bank_mask:0x3
	v_mov_b32_dpp v114, v118 row_ror:8 row_mask:0xf bank_mask:0x3
	v_mov_b32_dpp v115, v119 row_ror:8 row_mask:0xf bank_mask:0x3
	v_mov_b32_dpp v116, v148 quad_perm:[0,1,2,3] row_mask:0xf bank_mask:0xc
	v_mov_b32_dpp v117, v149 quad_perm:[0,1,2,3] row_mask:0xf bank_mask:0xc
	v_mov_b32_dpp v118, v150 quad_perm:[0,1,2,3] row_mask:0xf bank_mask:0xc
	v_mov_b32_dpp v119, v151 quad_perm:[0,1,2,3] row_mask:0xf bank_mask:0xc
	s_waitcnt vmcnt(17)
	v_pk_fma_f32 v[116:117], v[116:117], v[144:145], v[180:181]
	v_pk_fma_f32 v[118:119], v[118:119], v[146:147], v[182:183]
	v_pk_fma_f32 v[112:113], v[112:113], v[144:145], v[184:185]
	v_pk_fma_f32 v[114:115], v[114:115], v[146:147], v[186:187]
	s_add_u32 s98, s90, 0x10000
	s_addc_u32 s99, s91, 0
	global_store_dwordx4 v240, v[116:119], s[98:99]
	global_store_dwordx4 v242, v[112:115], s[98:99]
	s_add_u32 s100, s36, 0x10000
	s_addc_u32 s101, s37, 0
	global_load_dwordx4 v[180:183], v240, s[100:101] offset:512 nt
	global_load_dwordx4 v[184:187], v242, s[100:101] offset:512 nt
	v_mov_b32_dpp v148, v104 row_ror:8 row_mask:0xf bank_mask:0xf
	v_mov_b32_dpp v149, v105 row_ror:8 row_mask:0xf bank_mask:0xf
	v_mov_b32_dpp v150, v106 row_ror:8 row_mask:0xf bank_mask:0xf
	v_mov_b32_dpp v151, v107 row_ror:8 row_mask:0xf bank_mask:0xf
	v_mov_b32_dpp v104, v108 row_ror:8 row_mask:0xf bank_mask:0x3
	v_mov_b32_dpp v105, v109 row_ror:8 row_mask:0xf bank_mask:0x3
	v_mov_b32_dpp v106, v110 row_ror:8 row_mask:0xf bank_mask:0x3
	v_mov_b32_dpp v107, v111 row_ror:8 row_mask:0xf bank_mask:0x3
	v_mov_b32_dpp v108, v148 quad_perm:[0,1,2,3] row_mask:0xf bank_mask:0xc
	v_mov_b32_dpp v109, v149 quad_perm:[0,1,2,3] row_mask:0xf bank_mask:0xc
	v_mov_b32_dpp v110, v150 quad_perm:[0,1,2,3] row_mask:0xf bank_mask:0xc
	v_mov_b32_dpp v111, v151 quad_perm:[0,1,2,3] row_mask:0xf bank_mask:0xc
	s_waitcnt vmcnt(19)
;     __device__ __forceinline__ void operator()(const f32x4 (&acc)[2][2][4][2], const pg8::Unit& u, int wr, int wc, int fr, int fq) const {
;     ...
;         for (int bj = 0; bj < 2; ++bj) {
;             const int col = u.pn * 256 + bj * 128 + wc * 32 + 8 * fq;
;             const f32x4 g0 = *(const f32x4*)(gp + col) * coef, g1 = *(const f32x4*)(gp + col + 4) * coef;
; #pragma unroll
;             for (int ai = 0; ai < 2; ++ai)
; #pragma unroll
;                 for (int m = 0; m < 4; ++m) {
;                     const size_t off = (size_t)(row0 + ai * 128 + m * 16) * DM + col;
;                     const f32x4 x0 = *(const f32x4*)(base + off), x1 = *(const f32x4*)(base + off + 4);
;                     *(f32x4*)(out + off) = x0 + g0 * acc[ai][bj][m][0]; *(f32x4*)(out + off + 4) = x1 + g1 * acc[ai][bj][m][1];
;                     if (m & 1) asm volatile("" ::: "memory");
;                 }
	v_pk_fma_f32 v[108:109], v[108:109], v[144:145], v[188:189]
	v_pk_fma_f32 v[110:111], v[110:111], v[146:147], v[190:191]
	v_pk_fma_f32 v[104:105], v[104:105], v[144:145], v[192:193]
	v_pk_fma_f32 v[106:107], v[106:107], v[146:147], v[194:195]
	s_add_u32 s98, s90, 0x20000
	s_addc_u32 s99, s91, 0
	global_store_dwordx4 v240, v[108:111], s[98:99]
	global_store_dwordx4 v242, v[104:107], s[98:99]
	s_add_u32 s100, s36, 0x20000
	s_addc_u32 s101, s37, 0
	global_load_dwordx4 v[188:191], v240, s[100:101] offset:512 nt
	global_load_dwordx4 v[192:195], v242, s[100:101] offset:512 nt
	v_mov_b32_dpp v148, v96 row_ror:8 row_mask:0xf bank_mask:0xf
	v_mov_b32_dpp v149, v97 row_ror:8 row_mask:0xf bank_mask:0xf
	v_mov_b32_dpp v150, v98 row_ror:8 row_mask:0xf bank_mask:0xf
	v_mov_b32_dpp v151, v99 row_ror:8 row_mask:0xf bank_mask:0xf
	v_mov_b32_dpp v96, v100 row_ror:8 row_mask:0xf bank_mask:0x3
	v_mov_b32_dpp v97, v101 row_ror:8 row_mask:0xf bank_mask:0x3
	v_mov_b32_dpp v98, v102 row_ror:8 row_mask:0xf bank_mask:0x3
	v_mov_b32_dpp v99, v103 row_ror:8 row_mask:0xf bank_mask:0x3
	v_mov_b32_dpp v100, v148 quad_perm:[0,1,2,3] row_mask:0xf bank_mask:0xc
	v_mov_b32_dpp v101, v149 quad_perm:[0,1,2,3] row_mask:0xf bank_mask:0xc
	v_mov_b32_dpp v102, v150 quad_perm:[0,1,2,3] row_mask:0xf bank_mask:0xc
	v_mov_b32_dpp v103, v151 quad_perm:[0,1,2,3] row_mask:0xf bank_mask:0xc
	s_waitcnt vmcnt(21)
	v_pk_fma_f32 v[100:101], v[100:101], v[144:145], v[196:197]
	v_pk_fma_f32 v[102:103], v[102:103], v[146:147], v[198:199]
	v_pk_fma_f32 v[96:97], v[96:97], v[144:145], v[200:201]
	v_pk_fma_f32 v[98:99], v[98:99], v[146:147], v[202:203]
	s_add_u32 s98, s90, 0x30000
	s_addc_u32 s99, s91, 0
	global_store_dwordx4 v240, v[100:103], s[98:99]
	global_store_dwordx4 v242, v[96:99], s[98:99]
	s_add_u32 s100, s36, 0x30000
	s_addc_u32 s101, s37, 0
	global_load_dwordx4 v[196:199], v240, s[100:101] offset:512 nt
	global_load_dwordx4 v[200:203], v242, s[100:101] offset:512 nt
	v_mov_b32_dpp v148, v88 row_ror:8 row_mask:0xf bank_mask:0xf
	v_mov_b32_dpp v149, v89 row_ror:8 row_mask:0xf bank_mask:0xf
	v_mov_b32_dpp v150, v90 row_ror:8 row_mask:0xf bank_mask:0xf
	v_mov_b32_dpp v151, v91 row_ror:8 row_mask:0xf bank_mask:0xf
	v_mov_b32_dpp v88, v92 row_ror:8 row_mask:0xf bank_mask:0x3
	v_mov_b32_dpp v89, v93 row_ror:8 row_mask:0xf bank_mask:0x3
	v_mov_b32_dpp v90, v94 row_ror:8 row_mask:0xf bank_mask:0x3
	v_mov_b32_dpp v91, v95 row_ror:8 row_mask:0xf bank_mask:0x3
	v_mov_b32_dpp v92, v148 quad_perm:[0,1,2,3] row_mask:0xf bank_mask:0xc
	v_mov_b32_dpp v93, v149 quad_perm:[0,1,2,3] row_mask:0xf bank_mask:0xc
	v_mov_b32_dpp v94, v150 quad_perm:[0,1,2,3] row_mask:0xf bank_mask:0xc
	v_mov_b32_dpp v95, v151 quad_perm:[0,1,2,3] row_mask:0xf bank_mask:0xc
	s_waitcnt vmcnt(23)
	v_pk_fma_f32 v[92:93], v[92:93], v[144:145], v[208:209]
	v_pk_fma_f32 v[94:95], v[94:95], v[146:147], v[210:211]
	v_pk_fma_f32 v[88:89], v[88:89], v[144:145], v[212:213]
	v_pk_fma_f32 v[90:91], v[90:91], v[146:147], v[214:215]
	s_add_u32 s98, s90, 0x80000
	s_addc_u32 s99, s91, 0
	global_store_dwordx4 v240, v[92:95], s[98:99]
	global_store_dwordx4 v242, v[88:91], s[98:99]
	s_add_u32 s100, s36, 0x80000
	s_addc_u32 s101, s37, 0
	global_load_dwordx4 v[208:211], v240, s[100:101] offset:512 nt
	global_load_dwordx4 v[212:215], v242, s[100:101] offset:512 nt
	v_mov_b32_dpp v148, v80 row_ror:8 row_mask:0xf bank_mask:0xf
	v_mov_b32_dpp v149, v81 row_ror:8 row_mask:0xf bank_mask:0xf
	v_mov_b32_dpp v150, v82 row_ror:8 row_mask:0xf bank_mask:0xf
	v_mov_b32_dpp v151, v83 row_ror:8 row_mask:0xf bank_mask:0xf
	v_mov_b32_dpp v80, v84 row_ror:8 row_mask:0xf bank_mask:0x3
	v_mov_b32_dpp v81, v85 row_ror:8 row_mask:0xf bank_mask:0x3
	v_mov_b32_dpp v82, v86 row_ror:8 row_mask:0xf bank_mask:0x3
	v_mov_b32_dpp v83, v87 row_ror:8 row_mask:0xf bank_mask:0x3
	v_mov_b32_dpp v84, v148 quad_perm:[0,1,2,3] row_mask:0xf bank_mask:0xc
	v_mov_b32_dpp v85, v149 quad_perm:[0,1,2,3] row_mask:0xf bank_mask:0xc
	v_mov_b32_dpp v86, v150 quad_perm:[0,1,2,3] row_mask:0xf bank_mask:0xc
	v_mov_b32_dpp v87, v151 quad_perm:[0,1,2,3] row_mask:0xf bank_mask:0xc
	s_waitcnt vmcnt(25)
	v_pk_fma_f32 v[84:85], v[84:85], v[144:145], v[216:217]
	v_pk_fma_f32 v[86:87], v[86:87], v[146:147], v[218:219]
	v_pk_fma_f32 v[80:81], v[80:81], v[144:145], v[220:221]
	v_pk_fma_f32 v[82:83], v[82:83], v[146:147], v[222:223]
	s_add_u32 s98, s90, 0x90000
	s_addc_u32 s99, s91, 0
	global_store_dwordx4 v240, v[84:87], s[98:99]
	global_store_dwordx4 v242, v[80:83], s[98:99]
	s_add_u32 s100, s36, 0x90000
	s_addc_u32 s101, s37, 0
	global_load_dwordx4 v[216:219], v240, s[100:101] offset:512 nt
	global_load_dwordx4 v[220:223], v242, s[100:101] offset:512 nt
	v_mov_b32_dpp v148, v72 row_ror:8 row_mask:0xf bank_mask:0xf
	v_mov_b32_dpp v149, v73 row_ror:8 row_mask:0xf bank_mask:0xf
	v_mov_b32_dpp v150, v74 row_ror:8 row_mask:0xf bank_mask:0xf
	v_mov_b32_dpp v151, v75 row_ror:8 row_mask:0xf bank_mask:0xf
	v_mov_b32_dpp v72, v76 row_ror:8 row_mask:0xf bank_mask:0x3
	v_mov_b32_dpp v73, v77 row_ror:8 row_mask:0xf bank_mask:0x3
	v_mov_b32_dpp v74, v78 row_ror:8 row_mask:0xf bank_mask:0x3
	v_mov_b32_dpp v75, v79 row_ror:8 row_mask:0xf bank_mask:0x3
	v_mov_b32_dpp v76, v148 quad_perm:[0,1,2,3] row_mask:0xf bank_mask:0xc
	v_mov_b32_dpp v77, v149 quad_perm:[0,1,2,3] row_mask:0xf bank_mask:0xc
	v_mov_b32_dpp v78, v150 quad_perm:[0,1,2,3] row_mask:0xf bank_mask:0xc
	v_mov_b32_dpp v79, v151 quad_perm:[0,1,2,3] row_mask:0xf bank_mask:0xc
	s_waitcnt vmcnt(27)
;     __device__ __forceinline__ void operator()(const f32x4 (&acc)[2][2][4][2], const pg8::Unit& u, int wr, int wc, int fr, int fq) const {
;     ...
;         for (int bj = 0; bj < 2; ++bj) {
;             const int col = u.pn * 256 + bj * 128 + wc * 32 + 8 * fq;
;             const f32x4 g0 = *(const f32x4*)(gp + col) * coef, g1 = *(const f32x4*)(gp + col + 4) * coef;
; #pragma unroll
;             for (int ai = 0; ai < 2; ++ai)
; #pragma unroll
;                 for (int m = 0; m < 4; ++m) {
;                     const size_t off = (size_t)(row0 + ai * 128 + m * 16) * DM + col;
;                     const f32x4 x0 = *(const f32x4*)(base + off), x1 = *(const f32x4*)(base + off + 4);
;                     *(f32x4*)(out + off) = x0 + g0 * acc[ai][bj][m][0]; *(f32x4*)(out + off + 4) = x1 + g1 * acc[ai][bj][m][1];
;                     if (m & 1) asm volatile("" ::: "memory");
;                 }
	v_pk_fma_f32 v[76:77], v[76:77], v[144:145], v[224:225]
	v_pk_fma_f32 v[78:79], v[78:79], v[146:147], v[226:227]
	v_pk_fma_f32 v[72:73], v[72:73], v[144:145], v[228:229]
	v_pk_fma_f32 v[74:75], v[74:75], v[146:147], v[230:231]
	s_add_u32 s98, s90, 0xa0000
	s_addc_u32 s99, s91, 0
	global_store_dwordx4 v240, v[76:79], s[98:99]
	global_store_dwordx4 v242, v[72:75], s[98:99]
	s_add_u32 s100, s36, 0xa0000
	s_addc_u32 s101, s37, 0
	global_load_dwordx4 v[224:227], v240, s[100:101] offset:512 nt
	global_load_dwordx4 v[228:231], v242, s[100:101] offset:512 nt
	v_mov_b32_dpp v148, v64 row_ror:8 row_mask:0xf bank_mask:0xf
	v_mov_b32_dpp v149, v65 row_ror:8 row_mask:0xf bank_mask:0xf
	v_mov_b32_dpp v150, v66 row_ror:8 row_mask:0xf bank_mask:0xf
	v_mov_b32_dpp v151, v67 row_ror:8 row_mask:0xf bank_mask:0xf
	v_mov_b32_dpp v64, v68 row_ror:8 row_mask:0xf bank_mask:0x3
	v_mov_b32_dpp v65, v69 row_ror:8 row_mask:0xf bank_mask:0x3
	v_mov_b32_dpp v66, v70 row_ror:8 row_mask:0xf bank_mask:0x3
	v_mov_b32_dpp v67, v71 row_ror:8 row_mask:0xf bank_mask:0x3
	v_mov_b32_dpp v68, v148 quad_perm:[0,1,2,3] row_mask:0xf bank_mask:0xc
	v_mov_b32_dpp v69, v149 quad_perm:[0,1,2,3] row_mask:0xf bank_mask:0xc
	v_mov_b32_dpp v70, v150 quad_perm:[0,1,2,3] row_mask:0xf bank_mask:0xc
	v_mov_b32_dpp v71, v151 quad_perm:[0,1,2,3] row_mask:0xf bank_mask:0xc
	s_waitcnt vmcnt(29)
	v_pk_fma_f32 v[68:69], v[68:69], v[144:145], v[232:233]
	v_pk_fma_f32 v[70:71], v[70:71], v[146:147], v[234:235]
	v_pk_fma_f32 v[64:65], v[64:65], v[144:145], v[236:237]
	v_pk_fma_f32 v[66:67], v[66:67], v[146:147], v[238:239]
	s_add_u32 s98, s90, 0xb0000
	s_addc_u32 s99, s91, 0
	global_store_dwordx4 v240, v[68:71], s[98:99]
	global_store_dwordx4 v242, v[64:67], s[98:99]
	s_add_u32 s100, s36, 0xb0000
	s_addc_u32 s101, s37, 0
	global_load_dwordx4 v[232:235], v240, s[100:101] offset:512 nt
	global_load_dwordx4 v[236:239], v242, s[100:101] offset:512 nt
	v_mov_b32_dpp v148, v56 row_ror:8 row_mask:0xf bank_mask:0xf
	v_mov_b32_dpp v149, v57 row_ror:8 row_mask:0xf bank_mask:0xf
	v_mov_b32_dpp v150, v58 row_ror:8 row_mask:0xf bank_mask:0xf
	v_mov_b32_dpp v151, v59 row_ror:8 row_mask:0xf bank_mask:0xf
	v_mov_b32_dpp v56, v60 row_ror:8 row_mask:0xf bank_mask:0x3
	v_mov_b32_dpp v57, v61 row_ror:8 row_mask:0xf bank_mask:0x3
	v_mov_b32_dpp v58, v62 row_ror:8 row_mask:0xf bank_mask:0x3
	v_mov_b32_dpp v59, v63 row_ror:8 row_mask:0xf bank_mask:0x3
	v_mov_b32_dpp v60, v148 quad_perm:[0,1,2,3] row_mask:0xf bank_mask:0xc
	v_mov_b32_dpp v61, v149 quad_perm:[0,1,2,3] row_mask:0xf bank_mask:0xc
	v_mov_b32_dpp v62, v150 quad_perm:[0,1,2,3] row_mask:0xf bank_mask:0xc
	v_mov_b32_dpp v63, v151 quad_perm:[0,1,2,3] row_mask:0xf bank_mask:0xc
	s_waitcnt vmcnt(28)
	v_pk_mul_f32 v[120:121], v[120:121], 0.5 op_sel_hi:[1,0]
	v_pk_mul_f32 v[122:123], v[122:123], 0.5 op_sel_hi:[1,0]
	v_pk_fma_f32 v[60:61], v[60:61], v[120:121], v[172:173]
	v_pk_fma_f32 v[62:63], v[62:63], v[122:123], v[174:175]
	v_pk_fma_f32 v[56:57], v[56:57], v[120:121], v[176:177]
	v_pk_fma_f32 v[58:59], v[58:59], v[122:123], v[178:179]
	s_add_u32 s98, s90, 0x0
	s_addc_u32 s99, s91, 0
	global_store_dwordx4 v240, v[60:63], s[98:99] offset:512
	global_store_dwordx4 v242, v[56:59], s[98:99] offset:512
	v_mov_b32_dpp v148, v48 row_ror:8 row_mask:0xf bank_mask:0xf
	v_mov_b32_dpp v149, v49 row_ror:8 row_mask:0xf bank_mask:0xf
	v_mov_b32_dpp v150, v50 row_ror:8 row_mask:0xf bank_mask:0xf
	v_mov_b32_dpp v151, v51 row_ror:8 row_mask:0xf bank_mask:0xf
	v_mov_b32_dpp v48, v52 row_ror:8 row_mask:0xf bank_mask:0x3
	v_mov_b32_dpp v49, v53 row_ror:8 row_mask:0xf bank_mask:0x3
	v_mov_b32_dpp v50, v54 row_ror:8 row_mask:0xf bank_mask:0x3
	v_mov_b32_dpp v51, v55 row_ror:8 row_mask:0xf bank_mask:0x3
	v_mov_b32_dpp v52, v148 quad_perm:[0,1,2,3] row_mask:0xf bank_mask:0xc
	v_mov_b32_dpp v53, v149 quad_perm:[0,1,2,3] row_mask:0xf bank_mask:0xc
	v_mov_b32_dpp v54, v150 quad_perm:[0,1,2,3] row_mask:0xf bank_mask:0xc
	v_mov_b32_dpp v55, v151 quad_perm:[0,1,2,3] row_mask:0xf bank_mask:0xc
	s_waitcnt vmcnt(26)
	v_pk_fma_f32 v[52:53], v[52:53], v[120:121], v[180:181]
	v_pk_fma_f32 v[54:55], v[54:55], v[122:123], v[182:183]
	v_pk_fma_f32 v[48:49], v[48:49], v[120:121], v[184:185]
	v_pk_fma_f32 v[50:51], v[50:51], v[122:123], v[186:187]
	s_add_u32 s98, s90, 0x10000
	s_addc_u32 s99, s91, 0
	global_store_dwordx4 v240, v[52:55], s[98:99] offset:512
	global_store_dwordx4 v242, v[48:51], s[98:99] offset:512
	v_mov_b32_dpp v148, v40 row_ror:8 row_mask:0xf bank_mask:0xf
	v_mov_b32_dpp v149, v41 row_ror:8 row_mask:0xf bank_mask:0xf
	v_mov_b32_dpp v150, v42 row_ror:8 row_mask:0xf bank_mask:0xf
	v_mov_b32_dpp v151, v43 row_ror:8 row_mask:0xf bank_mask:0xf
	v_mov_b32_dpp v40, v44 row_ror:8 row_mask:0xf bank_mask:0x3
	v_mov_b32_dpp v41, v45 row_ror:8 row_mask:0xf bank_mask:0x3
	v_mov_b32_dpp v42, v46 row_ror:8 row_mask:0xf bank_mask:0x3
	v_mov_b32_dpp v43, v47 row_ror:8 row_mask:0xf bank_mask:0x3
	v_mov_b32_dpp v44, v148 quad_perm:[0,1,2,3] row_mask:0xf bank_mask:0xc
	v_mov_b32_dpp v45, v149 quad_perm:[0,1,2,3] row_mask:0xf bank_mask:0xc
	v_mov_b32_dpp v46, v150 quad_perm:[0,1,2,3] row_mask:0xf bank_mask:0xc
	v_mov_b32_dpp v47, v151 quad_perm:[0,1,2,3] row_mask:0xf bank_mask:0xc
	s_waitcnt vmcnt(24)
; #define PG8_BAR __builtin_amdgcn_s_barrier()
; template <class Epi, class Sched, bool ALIGN_EPI = false, bool SP2 = false>
; __device__ __forceinline__ void gemm_phase(PG8_LAS unsigned char* lds, const Gemm g, const Sched& S, const Epi& E, const int wid) {
;     ...
;         if (!has_next) break;
; #pragma unroll
;         for (int a = 0; a < 2; ++a)
; #pragma unroll
;             for (int b = 0; b < 2; ++b)
; #pragma unroll
;                 for (int m = 0; m < 4; ++m)
; #pragma unroll
;                     for (int n = 0; n < 2; ++n) acc[a][b][m][n] = (f32x4){0.f, 0.f, 0.f, 0.f};
;         cur = nxt; cA = nA; cB = nB; ++ui;
;         if constexpr (ALIGN_EPI) { if (wr == 1) PG8_BAR; }
;     __device__ __forceinline__ void operator()(const f32x4 (&acc)[2][2][4][2], const pg8::Unit& u, int wr, int wc, int fr, int fq) const {
;     ...
;         for (int bj = 0; bj < 2; ++bj) {
;             const int col = u.pn * 256 + bj * 128 + wc * 32 + 8 * fq;
;             const f32x4 g0 = *(const f32x4*)(gp + col) * coef, g1 = *(const f32x4*)(gp + col + 4) * coef;
; #pragma unroll
;             for (int ai = 0; ai < 2; ++ai)
; #pragma unroll
;                 for (int m = 0; m < 4; ++m) {
;                     const size_t off = (size_t)(row0 + ai * 128 + m * 16) * DM + col;
;                     const f32x4 x0 = *(const f32x4*)(base + off), x1 = *(const f32x4*)(base + off + 4);
;                     *(f32x4*)(out + off) = x0 + g0 * acc[ai][bj][m][0]; *(f32x4*)(out + off + 4) = x1 + g1 * acc[ai][bj][m][1];
;                     if (m & 1) asm volatile("" ::: "memory");
;                 }
;         }
	v_pk_fma_f32 v[44:45], v[44:45], v[120:121], v[188:189]
	v_pk_fma_f32 v[46:47], v[46:47], v[122:123], v[190:191]
	v_pk_fma_f32 v[40:41], v[40:41], v[120:121], v[192:193]
	v_pk_fma_f32 v[42:43], v[42:43], v[122:123], v[194:195]
	s_add_u32 s98, s90, 0x20000
	s_addc_u32 s99, s91, 0
	global_store_dwordx4 v240, v[44:47], s[98:99] offset:512
	global_store_dwordx4 v242, v[40:43], s[98:99] offset:512
	v_mov_b32_dpp v148, v32 row_ror:8 row_mask:0xf bank_mask:0xf
	v_mov_b32_dpp v149, v33 row_ror:8 row_mask:0xf bank_mask:0xf
	v_mov_b32_dpp v150, v34 row_ror:8 row_mask:0xf bank_mask:0xf
	v_mov_b32_dpp v151, v35 row_ror:8 row_mask:0xf bank_mask:0xf
	v_mov_b32_dpp v32, v36 row_ror:8 row_mask:0xf bank_mask:0x3
	v_mov_b32_dpp v33, v37 row_ror:8 row_mask:0xf bank_mask:0x3
	v_mov_b32_dpp v34, v38 row_ror:8 row_mask:0xf bank_mask:0x3
	v_mov_b32_dpp v35, v39 row_ror:8 row_mask:0xf bank_mask:0x3
	v_mov_b32_dpp v36, v148 quad_perm:[0,1,2,3] row_mask:0xf bank_mask:0xc
	v_mov_b32_dpp v37, v149 quad_perm:[0,1,2,3] row_mask:0xf bank_mask:0xc
	v_mov_b32_dpp v38, v150 quad_perm:[0,1,2,3] row_mask:0xf bank_mask:0xc
	v_mov_b32_dpp v39, v151 quad_perm:[0,1,2,3] row_mask:0xf bank_mask:0xc
	s_waitcnt vmcnt(22)
	v_pk_fma_f32 v[36:37], v[36:37], v[120:121], v[196:197]
	v_pk_fma_f32 v[38:39], v[38:39], v[122:123], v[198:199]
	v_pk_fma_f32 v[32:33], v[32:33], v[120:121], v[200:201]
	v_pk_fma_f32 v[34:35], v[34:35], v[122:123], v[202:203]
	s_add_u32 s98, s90, 0x30000
	s_addc_u32 s99, s91, 0
	global_store_dwordx4 v240, v[36:39], s[98:99] offset:512
	global_store_dwordx4 v242, v[32:35], s[98:99] offset:512
	v_mov_b32_dpp v148, v24 row_ror:8 row_mask:0xf bank_mask:0xf
	v_mov_b32_dpp v149, v25 row_ror:8 row_mask:0xf bank_mask:0xf
	v_mov_b32_dpp v150, v26 row_ror:8 row_mask:0xf bank_mask:0xf
	v_mov_b32_dpp v151, v27 row_ror:8 row_mask:0xf bank_mask:0xf
	v_mov_b32_dpp v24, v28 row_ror:8 row_mask:0xf bank_mask:0x3
	v_mov_b32_dpp v25, v29 row_ror:8 row_mask:0xf bank_mask:0x3
	v_mov_b32_dpp v26, v30 row_ror:8 row_mask:0xf bank_mask:0x3
	v_mov_b32_dpp v27, v31 row_ror:8 row_mask:0xf bank_mask:0x3
	v_mov_b32_dpp v28, v148 quad_perm:[0,1,2,3] row_mask:0xf bank_mask:0xc
	v_mov_b32_dpp v29, v149 quad_perm:[0,1,2,3] row_mask:0xf bank_mask:0xc
	v_mov_b32_dpp v30, v150 quad_perm:[0,1,2,3] row_mask:0xf bank_mask:0xc
	v_mov_b32_dpp v31, v151 quad_perm:[0,1,2,3] row_mask:0xf bank_mask:0xc
	s_waitcnt vmcnt(20)
	v_pk_fma_f32 v[28:29], v[28:29], v[120:121], v[208:209]
	v_pk_fma_f32 v[30:31], v[30:31], v[122:123], v[210:211]
	v_pk_fma_f32 v[24:25], v[24:25], v[120:121], v[212:213]
	v_pk_fma_f32 v[26:27], v[26:27], v[122:123], v[214:215]
	s_add_u32 s98, s90, 0x80000
	s_addc_u32 s99, s91, 0
	global_store_dwordx4 v240, v[28:31], s[98:99] offset:512
	global_store_dwordx4 v242, v[24:27], s[98:99] offset:512
	v_mov_b32_dpp v148, v16 row_ror:8 row_mask:0xf bank_mask:0xf
	v_mov_b32_dpp v149, v17 row_ror:8 row_mask:0xf bank_mask:0xf
	v_mov_b32_dpp v150, v18 row_ror:8 row_mask:0xf bank_mask:0xf
	v_mov_b32_dpp v151, v19 row_ror:8 row_mask:0xf bank_mask:0xf
	v_mov_b32_dpp v16, v20 row_ror:8 row_mask:0xf bank_mask:0x3
	v_mov_b32_dpp v17, v21 row_ror:8 row_mask:0xf bank_mask:0x3
	v_mov_b32_dpp v18, v22 row_ror:8 row_mask:0xf bank_mask:0x3
	v_mov_b32_dpp v19, v23 row_ror:8 row_mask:0xf bank_mask:0x3
	v_mov_b32_dpp v20, v148 quad_perm:[0,1,2,3] row_mask:0xf bank_mask:0xc
	v_mov_b32_dpp v21, v149 quad_perm:[0,1,2,3] row_mask:0xf bank_mask:0xc
	v_mov_b32_dpp v22, v150 quad_perm:[0,1,2,3] row_mask:0xf bank_mask:0xc
	v_mov_b32_dpp v23, v151 quad_perm:[0,1,2,3] row_mask:0xf bank_mask:0xc
	s_waitcnt vmcnt(18)
	v_pk_fma_f32 v[20:21], v[20:21], v[120:121], v[216:217]
	v_pk_fma_f32 v[22:23], v[22:23], v[122:123], v[218:219]
	v_pk_fma_f32 v[16:17], v[16:17], v[120:121], v[220:221]
	v_pk_fma_f32 v[18:19], v[18:19], v[122:123], v[222:223]
	s_add_u32 s98, s90, 0x90000
	s_addc_u32 s99, s91, 0
	global_store_dwordx4 v240, v[20:23], s[98:99] offset:512
	global_store_dwordx4 v242, v[16:19], s[98:99] offset:512
	v_mov_b32_dpp v148, v8 row_ror:8 row_mask:0xf bank_mask:0xf
	v_mov_b32_dpp v149, v9 row_ror:8 row_mask:0xf bank_mask:0xf
	v_mov_b32_dpp v150, v10 row_ror:8 row_mask:0xf bank_mask:0xf
	v_mov_b32_dpp v151, v11 row_ror:8 row_mask:0xf bank_mask:0xf
	v_mov_b32_dpp v8, v12 row_ror:8 row_mask:0xf bank_mask:0x3
	v_mov_b32_dpp v9, v13 row_ror:8 row_mask:0xf bank_mask:0x3
	v_mov_b32_dpp v10, v14 row_ror:8 row_mask:0xf bank_mask:0x3
	v_mov_b32_dpp v11, v15 row_ror:8 row_mask:0xf bank_mask:0x3
	v_mov_b32_dpp v12, v148 quad_perm:[0,1,2,3] row_mask:0xf bank_mask:0xc
	v_mov_b32_dpp v13, v149 quad_perm:[0,1,2,3] row_mask:0xf bank_mask:0xc
	v_mov_b32_dpp v14, v150 quad_perm:[0,1,2,3] row_mask:0xf bank_mask:0xc
	v_mov_b32_dpp v15, v151 quad_perm:[0,1,2,3] row_mask:0xf bank_mask:0xc
	s_waitcnt vmcnt(16)
	v_pk_fma_f32 v[12:13], v[12:13], v[120:121], v[224:225]
	v_pk_fma_f32 v[14:15], v[14:15], v[122:123], v[226:227]
	v_pk_fma_f32 v[8:9], v[8:9], v[120:121], v[228:229]
	v_pk_fma_f32 v[10:11], v[10:11], v[122:123], v[230:231]
	s_add_u32 s98, s90, 0xa0000
	s_addc_u32 s99, s91, 0
	global_store_dwordx4 v240, v[12:15], s[98:99] offset:512
	global_store_dwordx4 v242, v[8:11], s[98:99] offset:512
	v_mov_b32_dpp v148, v0 row_ror:8 row_mask:0xf bank_mask:0xf
	v_mov_b32_dpp v149, v1 row_ror:8 row_mask:0xf bank_mask:0xf
	v_mov_b32_dpp v150, v2 row_ror:8 row_mask:0xf bank_mask:0xf
	v_mov_b32_dpp v151, v3 row_ror:8 row_mask:0xf bank_mask:0xf
	v_mov_b32_dpp v0, v4 row_ror:8 row_mask:0xf bank_mask:0x3
	v_mov_b32_dpp v1, v5 row_ror:8 row_mask:0xf bank_mask:0x3
	v_mov_b32_dpp v2, v6 row_ror:8 row_mask:0xf bank_mask:0x3
	v_mov_b32_dpp v3, v7 row_ror:8 row_mask:0xf bank_mask:0x3
	v_mov_b32_dpp v4, v148 quad_perm:[0,1,2,3] row_mask:0xf bank_mask:0xc
	v_mov_b32_dpp v5, v149 quad_perm:[0,1,2,3] row_mask:0xf bank_mask:0xc
	v_mov_b32_dpp v6, v150 quad_perm:[0,1,2,3] row_mask:0xf bank_mask:0xc
	v_mov_b32_dpp v7, v151 quad_perm:[0,1,2,3] row_mask:0xf bank_mask:0xc
	s_waitcnt vmcnt(14)
	v_pk_fma_f32 v[4:5], v[4:5], v[120:121], v[232:233]
	v_pk_fma_f32 v[6:7], v[6:7], v[122:123], v[234:235]
	v_pk_fma_f32 v[0:1], v[0:1], v[120:121], v[236:237]
	v_pk_fma_f32 v[2:3], v[2:3], v[122:123], v[238:239]
	s_add_u32 s98, s90, 0xb0000
	s_addc_u32 s99, s91, 0
	global_store_dwordx4 v240, v[4:7], s[98:99] offset:512
	global_store_dwordx4 v242, v[0:3], s[98:99] offset:512
	s_and_b64 vcc, exec, s[6:7]
	s_mov_b64 s[24:25], -1
	s_cbranch_vccnz .LBB0_220
	s_andn2_b64 vcc, exec, s[10:11]
	s_cbranch_vccnz .LBB0_219
	s_barrier
	s_branch .LBB0_219

;     __device__ __forceinline__ void operator()(const f32x4 (&acc)[2][2][4][2], const pg8::Unit& u, int wr, int wc, int fr, int fq) const {
;         const int row0 = u.pm * 256 + wr * 64 + fr; const float* gp = gate + (size_t)(u.pm >> 5) * NMOD;
; #pragma unroll
;         for (int bj = 0; bj < 2; ++bj) {
;             const int col = u.pn * 256 + bj * 128 + wc * 32 + 8 * fq;
;             const f32x4 g0 = *(const f32x4*)(gp + col) * coef, g1 = *(const f32x4*)(gp + col + 4) * coef;
; #pragma unroll
;             for (int ai = 0; ai < 2; ++ai)
; #pragma unroll
;                 for (int m = 0; m < 4; ++m) {
;                     const size_t off = (size_t)(row0 + ai * 128 + m * 16) * DM + col;
;                     const f32x4 x0 = *(const f32x4*)(base + off), x1 = *(const f32x4*)(base + off + 4);
;                     *(f32x4*)(out + off) = x0 + g0 * acc[ai][bj][m][0]; *(f32x4*)(out + off + 4) = x1 + g1 * acc[ai][bj][m][1];
.LBB0_1173:
	v_and_b32_e32 v243, 8, v164
	v_sub_u32_e32 v240, v164, v243
	v_lshrrev_b32_e32 v243, 1, v243
	v_add_u32_e32 v241, v167, v243
	v_lshl_add_u32 v240, s28, 8, v240
	v_lshl_add_u32 v241, s53, 8, v241
	v_lshlrev_b32_e32 v240, 10, v240
	v_add_lshl_u32 v240, v240, v241, 2
	v_lshlrev_b32_e32 v241, 2, v241
	v_add_u32_e32 v242, 0x8000, v240
	s_ashr_i32 s98, s28, 5
	s_mul_i32 s98, s98, 0x9000
	s_add_u32 s98, s45, s98
	s_addc_u32 s99, s46, 0
	global_load_dwordx4 v[152:155], v241, s[98:99]
	s_add_u32 s100, s90, 0x0
	s_addc_u32 s101, s91, 0
	global_load_dwordx4 v[172:175], v240, s[100:101] nt
	global_load_dwordx4 v[176:179], v242, s[100:101] nt
	s_add_u32 s100, s90, 0x10000
	s_addc_u32 s101, s91, 0
	global_load_dwordx4 v[180:183], v240, s[100:101] nt
	global_load_dwordx4 v[184:187], v242, s[100:101] nt
	s_add_u32 s100, s90, 0x20000
	s_addc_u32 s101, s91, 0
	global_load_dwordx4 v[188:191], v240, s[100:101] nt
	global_load_dwordx4 v[192:195], v242, s[100:101] nt
	s_add_u32 s100, s90, 0x30000
	s_addc_u32 s101, s91, 0
	global_load_dwordx4 v[196:199], v240, s[100:101] nt
	global_load_dwordx4 v[200:203], v242, s[100:101] nt
	s_add_u32 s100, s90, 0x80000
	s_addc_u32 s101, s91, 0
	global_load_dwordx4 v[208:211], v240, s[100:101] nt
	global_load_dwordx4 v[212:215], v242, s[100:101] nt
	s_add_u32 s100, s90, 0x90000
	s_addc_u32 s101, s91, 0
	global_load_dwordx4 v[216:219], v240, s[100:101] nt
	global_load_dwordx4 v[220:223], v242, s[100:101] nt
	s_add_u32 s100, s90, 0xa0000
	s_addc_u32 s101, s91, 0
	global_load_dwordx4 v[224:227], v240, s[100:101] nt
	global_load_dwordx4 v[228:231], v242, s[100:101] nt
	s_add_u32 s100, s90, 0xb0000
	s_addc_u32 s101, s91, 0
	global_load_dwordx4 v[232:235], v240, s[100:101] nt
	global_load_dwordx4 v[236:239], v242, s[100:101] nt
	v_mov_b32_dpp v156, v120 row_ror:8 row_mask:0xf bank_mask:0xf
	v_mov_b32_dpp v157, v121 row_ror:8 row_mask:0xf bank_mask:0xf
	v_mov_b32_dpp v158, v122 row_ror:8 row_mask:0xf bank_mask:0xf
	v_mov_b32_dpp v159, v123 row_ror:8 row_mask:0xf bank_mask:0xf
	v_mov_b32_dpp v120, v124 row_ror:8 row_mask:0xf bank_mask:0x3
	v_mov_b32_dpp v121, v125 row_ror:8 row_mask:0xf bank_mask:0x3
	v_mov_b32_dpp v122, v126 row_ror:8 row_mask:0xf bank_mask:0x3
	v_mov_b32_dpp v123, v127 row_ror:8 row_mask:0xf bank_mask:0x3
	v_mov_b32_dpp v124, v156 quad_perm:[0,1,2,3] row_mask:0xf bank_mask:0xc
	v_mov_b32_dpp v125, v157 quad_perm:[0,1,2,3] row_mask:0xf bank_mask:0xc
	v_mov_b32_dpp v126, v158 quad_perm:[0,1,2,3] row_mask:0xf bank_mask:0xc
	v_mov_b32_dpp v127, v159 quad_perm:[0,1,2,3] row_mask:0xf bank_mask:0xc
	s_waitcnt vmcnt(16)
	s_waitcnt vmcnt(14)
	v_pk_fma_f32 v[124:125], v[124:125], v[152:153], v[172:173]
	v_pk_fma_f32 v[126:127], v[126:127], v[154:155], v[174:175]
	v_pk_fma_f32 v[120:121], v[120:121], v[152:153], v[176:177]
	v_pk_fma_f32 v[122:123], v[122:123], v[154:155], v[178:179]
	s_add_u32 s98, s90, 0x0
	s_addc_u32 s99, s91, 0
	global_store_dwordx4 v240, v[124:127], s[98:99]
	global_store_dwordx4 v242, v[120:123], s[98:99]
	s_add_u32 s100, s90, 0x0
	s_addc_u32 s101, s91, 0
	global_load_dwordx4 v[172:175], v240, s[100:101] offset:512 nt
	global_load_dwordx4 v[176:179], v242, s[100:101] offset:512 nt
	s_ashr_i32 s98, s28, 5
	s_mul_i32 s98, s98, 0x9000
	s_add_u32 s98, s45, s98
	s_addc_u32 s99, s46, 0
	global_load_dwordx4 v[120:123], v241, s[98:99] offset:512
	v_mov_b32_dpp v156, v112 row_ror:8 row_mask:0xf bank_mask:0xf
	v_mov_b32_dpp v157, v113 row_ror:8 row_mask:0xf bank_mask:0xf
	v_mov_b32_dpp v158, v114 row_ror:8 row_mask:0xf bank_mask:0xf
	v_mov_b32_dpp v159, v115 row_ror:8 row_mask:0xf bank_mask:0xf
	v_mov_b32_dpp v112, v116 row_ror:8 row_mask:0xf bank_mask:0x3
	v_mov_b32_dpp v113, v117 row_ror:8 row_mask:0xf bank_mask:0x3
	v_mov_b32_dpp v114, v118 row_ror:8 row_mask:0xf bank_mask:0x3
	v_mov_b32_dpp v115, v119 row_ror:8 row_mask:0xf bank_mask:0x3
	v_mov_b32_dpp v116, v156 quad_perm:[0,1,2,3] row_mask:0xf bank_mask:0xc
	v_mov_b32_dpp v117, v157 quad_perm:[0,1,2,3] row_mask:0xf bank_mask:0xc
	v_mov_b32_dpp v118, v158 quad_perm:[0,1,2,3] row_mask:0xf bank_mask:0xc
	v_mov_b32_dpp v119, v159 quad_perm:[0,1,2,3] row_mask:0xf bank_mask:0xc
	s_waitcnt vmcnt(17)
	v_pk_fma_f32 v[116:117], v[116:117], v[152:153], v[180:181]
	v_pk_fma_f32 v[118:119], v[118:119], v[154:155], v[182:183]
	v_pk_fma_f32 v[112:113], v[112:113], v[152:153], v[184:185]
	v_pk_fma_f32 v[114:115], v[114:115], v[154:155], v[186:187]
	s_add_u32 s98, s90, 0x10000
	s_addc_u32 s99, s91, 0
	global_store_dwordx4 v240, v[116:119], s[98:99]
	global_store_dwordx4 v242, v[112:115], s[98:99]
	s_add_u32 s100, s90, 0x10000
	s_addc_u32 s101, s91, 0
	global_load_dwordx4 v[180:183], v240, s[100:101] offset:512 nt
	global_load_dwordx4 v[184:187], v242, s[100:101] offset:512 nt
	v_mov_b32_dpp v156, v104 row_ror:8 row_mask:0xf bank_mask:0xf
	v_mov_b32_dpp v157, v105 row_ror:8 row_mask:0xf bank_mask:0xf
	v_mov_b32_dpp v158, v106 row_ror:8 row_mask:0xf bank_mask:0xf
	v_mov_b32_dpp v159, v107 row_ror:8 row_mask:0xf bank_mask:0xf
	v_mov_b32_dpp v104, v108 row_ror:8 row_mask:0xf bank_mask:0x3
	v_mov_b32_dpp v105, v109 row_ror:8 row_mask:0xf bank_mask:0x3
	v_mov_b32_dpp v106, v110 row_ror:8 row_mask:0xf bank_mask:0x3
	v_mov_b32_dpp v107, v111 row_ror:8 row_mask:0xf bank_mask:0x3
	v_mov_b32_dpp v108, v156 quad_perm:[0,1,2,3] row_mask:0xf bank_mask:0xc
	v_mov_b32_dpp v109, v157 quad_perm:[0,1,2,3] row_mask:0xf bank_mask:0xc
	v_mov_b32_dpp v110, v158 quad_perm:[0,1,2,3] row_mask:0xf bank_mask:0xc
	v_mov_b32_dpp v111, v159 quad_perm:[0,1,2,3] row_mask:0xf bank_mask:0xc
	s_waitcnt vmcnt(19)
;     __device__ __forceinline__ void operator()(const f32x4 (&acc)[2][2][4][2], const pg8::Unit& u, int wr, int wc, int fr, int fq) const {
;     ...
;         for (int bj = 0; bj < 2; ++bj) {
;             const int col = u.pn * 256 + bj * 128 + wc * 32 + 8 * fq;
;             const f32x4 g0 = *(const f32x4*)(gp + col) * coef, g1 = *(const f32x4*)(gp + col + 4) * coef;
; #pragma unroll
;             for (int ai = 0; ai < 2; ++ai)
; #pragma unroll
;                 for (int m = 0; m < 4; ++m) {
;                     const size_t off = (size_t)(row0 + ai * 128 + m * 16) * DM + col;
;                     const f32x4 x0 = *(const f32x4*)(base + off), x1 = *(const f32x4*)(base + off + 4);
;                     *(f32x4*)(out + off) = x0 + g0 * acc[ai][bj][m][0]; *(f32x4*)(out + off + 4) = x1 + g1 * acc[ai][bj][m][1];
;                     if (m & 1) asm volatile("" ::: "memory");
;                 }
	v_pk_fma_f32 v[108:109], v[108:109], v[152:153], v[188:189]
	v_pk_fma_f32 v[110:111], v[110:111], v[154:155], v[190:191]
	v_pk_fma_f32 v[104:105], v[104:105], v[152:153], v[192:193]
	v_pk_fma_f32 v[106:107], v[106:107], v[154:155], v[194:195]
	s_add_u32 s98, s90, 0x20000
	s_addc_u32 s99, s91, 0
	global_store_dwordx4 v240, v[108:111], s[98:99]
	global_store_dwordx4 v242, v[104:107], s[98:99]
	s_add_u32 s100, s90, 0x20000
	s_addc_u32 s101, s91, 0
	global_load_dwordx4 v[188:191], v240, s[100:101] offset:512 nt
	global_load_dwordx4 v[192:195], v242, s[100:101] offset:512 nt
	v_mov_b32_dpp v156, v96 row_ror:8 row_mask:0xf bank_mask:0xf
	v_mov_b32_dpp v157, v97 row_ror:8 row_mask:0xf bank_mask:0xf
	v_mov_b32_dpp v158, v98 row_ror:8 row_mask:0xf bank_mask:0xf
	v_mov_b32_dpp v159, v99 row_ror:8 row_mask:0xf bank_mask:0xf
	v_mov_b32_dpp v96, v100 row_ror:8 row_mask:0xf bank_mask:0x3
	v_mov_b32_dpp v97, v101 row_ror:8 row_mask:0xf bank_mask:0x3
	v_mov_b32_dpp v98, v102 row_ror:8 row_mask:0xf bank_mask:0x3
	v_mov_b32_dpp v99, v103 row_ror:8 row_mask:0xf bank_mask:0x3
	v_mov_b32_dpp v100, v156 quad_perm:[0,1,2,3] row_mask:0xf bank_mask:0xc
	v_mov_b32_dpp v101, v157 quad_perm:[0,1,2,3] row_mask:0xf bank_mask:0xc
	v_mov_b32_dpp v102, v158 quad_perm:[0,1,2,3] row_mask:0xf bank_mask:0xc
	v_mov_b32_dpp v103, v159 quad_perm:[0,1,2,3] row_mask:0xf bank_mask:0xc
	s_waitcnt vmcnt(21)
	v_pk_fma_f32 v[100:101], v[100:101], v[152:153], v[196:197]
	v_pk_fma_f32 v[102:103], v[102:103], v[154:155], v[198:199]
	v_pk_fma_f32 v[96:97], v[96:97], v[152:153], v[200:201]
	v_pk_fma_f32 v[98:99], v[98:99], v[154:155], v[202:203]
	s_add_u32 s98, s90, 0x30000
	s_addc_u32 s99, s91, 0
	global_store_dwordx4 v240, v[100:103], s[98:99]
	global_store_dwordx4 v242, v[96:99], s[98:99]
	s_add_u32 s100, s90, 0x30000
	s_addc_u32 s101, s91, 0
	global_load_dwordx4 v[196:199], v240, s[100:101] offset:512 nt
	global_load_dwordx4 v[200:203], v242, s[100:101] offset:512 nt
	v_mov_b32_dpp v156, v88 row_ror:8 row_mask:0xf bank_mask:0xf
	v_mov_b32_dpp v157, v89 row_ror:8 row_mask:0xf bank_mask:0xf
	v_mov_b32_dpp v158, v90 row_ror:8 row_mask:0xf bank_mask:0xf
	v_mov_b32_dpp v159, v91 row_ror:8 row_mask:0xf bank_mask:0xf
	v_mov_b32_dpp v88, v92 row_ror:8 row_mask:0xf bank_mask:0x3
	v_mov_b32_dpp v89, v93 row_ror:8 row_mask:0xf bank_mask:0x3
	v_mov_b32_dpp v90, v94 row_ror:8 row_mask:0xf bank_mask:0x3
	v_mov_b32_dpp v91, v95 row_ror:8 row_mask:0xf bank_mask:0x3
	v_mov_b32_dpp v92, v156 quad_perm:[0,1,2,3] row_mask:0xf bank_mask:0xc
	v_mov_b32_dpp v93, v157 quad_perm:[0,1,2,3] row_mask:0xf bank_mask:0xc
	v_mov_b32_dpp v94, v158 quad_perm:[0,1,2,3] row_mask:0xf bank_mask:0xc
	v_mov_b32_dpp v95, v159 quad_perm:[0,1,2,3] row_mask:0xf bank_mask:0xc
	s_waitcnt vmcnt(23)
	v_pk_fma_f32 v[92:93], v[92:93], v[152:153], v[208:209]
	v_pk_fma_f32 v[94:95], v[94:95], v[154:155], v[210:211]
	v_pk_fma_f32 v[88:89], v[88:89], v[152:153], v[212:213]
	v_pk_fma_f32 v[90:91], v[90:91], v[154:155], v[214:215]
	s_add_u32 s98, s90, 0x80000
	s_addc_u32 s99, s91, 0
	global_store_dwordx4 v240, v[92:95], s[98:99]
	global_store_dwordx4 v242, v[88:91], s[98:99]
	s_add_u32 s100, s90, 0x80000
	s_addc_u32 s101, s91, 0
	global_load_dwordx4 v[208:211], v240, s[100:101] offset:512 nt
	global_load_dwordx4 v[212:215], v242, s[100:101] offset:512 nt
	v_mov_b32_dpp v156, v80 row_ror:8 row_mask:0xf bank_mask:0xf
	v_mov_b32_dpp v157, v81 row_ror:8 row_mask:0xf bank_mask:0xf
	v_mov_b32_dpp v158, v82 row_ror:8 row_mask:0xf bank_mask:0xf
	v_mov_b32_dpp v159, v83 row_ror:8 row_mask:0xf bank_mask:0xf
	v_mov_b32_dpp v80, v84 row_ror:8 row_mask:0xf bank_mask:0x3
	v_mov_b32_dpp v81, v85 row_ror:8 row_mask:0xf bank_mask:0x3
	v_mov_b32_dpp v82, v86 row_ror:8 row_mask:0xf bank_mask:0x3
	v_mov_b32_dpp v83, v87 row_ror:8 row_mask:0xf bank_mask:0x3
	v_mov_b32_dpp v84, v156 quad_perm:[0,1,2,3] row_mask:0xf bank_mask:0xc
	v_mov_b32_dpp v85, v157 quad_perm:[0,1,2,3] row_mask:0xf bank_mask:0xc
	v_mov_b32_dpp v86, v158 quad_perm:[0,1,2,3] row_mask:0xf bank_mask:0xc
	v_mov_b32_dpp v87, v159 quad_perm:[0,1,2,3] row_mask:0xf bank_mask:0xc
	s_waitcnt vmcnt(25)
	v_pk_fma_f32 v[84:85], v[84:85], v[152:153], v[216:217]
	v_pk_fma_f32 v[86:87], v[86:87], v[154:155], v[218:219]
	v_pk_fma_f32 v[80:81], v[80:81], v[152:153], v[220:221]
	v_pk_fma_f32 v[82:83], v[82:83], v[154:155], v[222:223]
	s_add_u32 s98, s90, 0x90000
	s_addc_u32 s99, s91, 0
	global_store_dwordx4 v240, v[84:87], s[98:99]
	global_store_dwordx4 v242, v[80:83], s[98:99]
	s_add_u32 s100, s90, 0x90000
	s_addc_u32 s101, s91, 0
	global_load_dwordx4 v[216:219], v240, s[100:101] offset:512 nt
	global_load_dwordx4 v[220:223], v242, s[100:101] offset:512 nt
	v_mov_b32_dpp v156, v72 row_ror:8 row_mask:0xf bank_mask:0xf
	v_mov_b32_dpp v157, v73 row_ror:8 row_mask:0xf bank_mask:0xf
	v_mov_b32_dpp v158, v74 row_ror:8 row_mask:0xf bank_mask:0xf
	v_mov_b32_dpp v159, v75 row_ror:8 row_mask:0xf bank_mask:0xf
	v_mov_b32_dpp v72, v76 row_ror:8 row_mask:0xf bank_mask:0x3
	v_mov_b32_dpp v73, v77 row_ror:8 row_mask:0xf bank_mask:0x3
	v_mov_b32_dpp v74, v78 row_ror:8 row_mask:0xf bank_mask:0x3
	v_mov_b32_dpp v75, v79 row_ror:8 row_mask:0xf bank_mask:0x3
	v_mov_b32_dpp v76, v156 quad_perm:[0,1,2,3] row_mask:0xf bank_mask:0xc
	v_mov_b32_dpp v77, v157 quad_perm:[0,1,2,3] row_mask:0xf bank_mask:0xc
	v_mov_b32_dpp v78, v158 quad_perm:[0,1,2,3] row_mask:0xf bank_mask:0xc
	v_mov_b32_dpp v79, v159 quad_perm:[0,1,2,3] row_mask:0xf bank_mask:0xc
	s_waitcnt vmcnt(27)
;     __device__ __forceinline__ void operator()(const f32x4 (&acc)[2][2][4][2], const pg8::Unit& u, int wr, int wc, int fr, int fq) const {
;     ...
;         for (int bj = 0; bj < 2; ++bj) {
;             const int col = u.pn * 256 + bj * 128 + wc * 32 + 8 * fq;
;             const f32x4 g0 = *(const f32x4*)(gp + col) * coef, g1 = *(const f32x4*)(gp + col + 4) * coef;
; #pragma unroll
;             for (int ai = 0; ai < 2; ++ai)
; #pragma unroll
;                 for (int m = 0; m < 4; ++m) {
;                     const size_t off = (size_t)(row0 + ai * 128 + m * 16) * DM + col;
;                     const f32x4 x0 = *(const f32x4*)(base + off), x1 = *(const f32x4*)(base + off + 4);
;                     *(f32x4*)(out + off) = x0 + g0 * acc[ai][bj][m][0]; *(f32x4*)(out + off + 4) = x1 + g1 * acc[ai][bj][m][1];
;                     if (m & 1) asm volatile("" ::: "memory");
;                 }
	v_pk_fma_f32 v[76:77], v[76:77], v[152:153], v[224:225]
	v_pk_fma_f32 v[78:79], v[78:79], v[154:155], v[226:227]
	v_pk_fma_f32 v[72:73], v[72:73], v[152:153], v[228:229]
	v_pk_fma_f32 v[74:75], v[74:75], v[154:155], v[230:231]
	s_add_u32 s98, s90, 0xa0000
	s_addc_u32 s99, s91, 0
	global_store_dwordx4 v240, v[76:79], s[98:99]
	global_store_dwordx4 v242, v[72:75], s[98:99]
	s_add_u32 s100, s90, 0xa0000
	s_addc_u32 s101, s91, 0
	global_load_dwordx4 v[224:227], v240, s[100:101] offset:512 nt
	global_load_dwordx4 v[228:231], v242, s[100:101] offset:512 nt
	v_mov_b32_dpp v156, v64 row_ror:8 row_mask:0xf bank_mask:0xf
	v_mov_b32_dpp v157, v65 row_ror:8 row_mask:0xf bank_mask:0xf
	v_mov_b32_dpp v158, v66 row_ror:8 row_mask:0xf bank_mask:0xf
	v_mov_b32_dpp v159, v67 row_ror:8 row_mask:0xf bank_mask:0xf
	v_mov_b32_dpp v64, v68 row_ror:8 row_mask:0xf bank_mask:0x3
	v_mov_b32_dpp v65, v69 row_ror:8 row_mask:0xf bank_mask:0x3
	v_mov_b32_dpp v66, v70 row_ror:8 row_mask:0xf bank_mask:0x3
	v_mov_b32_dpp v67, v71 row_ror:8 row_mask:0xf bank_mask:0x3
	v_mov_b32_dpp v68, v156 quad_perm:[0,1,2,3] row_mask:0xf bank_mask:0xc
	v_mov_b32_dpp v69, v157 quad_perm:[0,1,2,3] row_mask:0xf bank_mask:0xc
	v_mov_b32_dpp v70, v158 quad_perm:[0,1,2,3] row_mask:0xf bank_mask:0xc
	v_mov_b32_dpp v71, v159 quad_perm:[0,1,2,3] row_mask:0xf bank_mask:0xc
	s_waitcnt vmcnt(29)
	v_pk_fma_f32 v[68:69], v[68:69], v[152:153], v[232:233]
	v_pk_fma_f32 v[70:71], v[70:71], v[154:155], v[234:235]
	v_pk_fma_f32 v[64:65], v[64:65], v[152:153], v[236:237]
	v_pk_fma_f32 v[66:67], v[66:67], v[154:155], v[238:239]
	s_add_u32 s98, s90, 0xb0000
	s_addc_u32 s99, s91, 0
	global_store_dwordx4 v240, v[68:71], s[98:99]
	global_store_dwordx4 v242, v[64:67], s[98:99]
	s_add_u32 s100, s90, 0xb0000
	s_addc_u32 s101, s91, 0
	global_load_dwordx4 v[232:235], v240, s[100:101] offset:512 nt
	global_load_dwordx4 v[236:239], v242, s[100:101] offset:512 nt
	v_mov_b32_dpp v156, v56 row_ror:8 row_mask:0xf bank_mask:0xf
	v_mov_b32_dpp v157, v57 row_ror:8 row_mask:0xf bank_mask:0xf
	v_mov_b32_dpp v158, v58 row_ror:8 row_mask:0xf bank_mask:0xf
	v_mov_b32_dpp v159, v59 row_ror:8 row_mask:0xf bank_mask:0xf
	v_mov_b32_dpp v56, v60 row_ror:8 row_mask:0xf bank_mask:0x3
	v_mov_b32_dpp v57, v61 row_ror:8 row_mask:0xf bank_mask:0x3
	v_mov_b32_dpp v58, v62 row_ror:8 row_mask:0xf bank_mask:0x3
	v_mov_b32_dpp v59, v63 row_ror:8 row_mask:0xf bank_mask:0x3
	v_mov_b32_dpp v60, v156 quad_perm:[0,1,2,3] row_mask:0xf bank_mask:0xc
	v_mov_b32_dpp v61, v157 quad_perm:[0,1,2,3] row_mask:0xf bank_mask:0xc
	v_mov_b32_dpp v62, v158 quad_perm:[0,1,2,3] row_mask:0xf bank_mask:0xc
	v_mov_b32_dpp v63, v159 quad_perm:[0,1,2,3] row_mask:0xf bank_mask:0xc
	s_waitcnt vmcnt(28)
	v_pk_fma_f32 v[60:61], v[60:61], v[120:121], v[172:173]
	v_pk_fma_f32 v[62:63], v[62:63], v[122:123], v[174:175]
	v_pk_fma_f32 v[56:57], v[56:57], v[120:121], v[176:177]
	v_pk_fma_f32 v[58:59], v[58:59], v[122:123], v[178:179]
	s_add_u32 s98, s90, 0x0
	s_addc_u32 s99, s91, 0
	global_store_dwordx4 v240, v[60:63], s[98:99] offset:512
	global_store_dwordx4 v242, v[56:59], s[98:99] offset:512
	v_mov_b32_dpp v156, v48 row_ror:8 row_mask:0xf bank_mask:0xf
	v_mov_b32_dpp v157, v49 row_ror:8 row_mask:0xf bank_mask:0xf
	v_mov_b32_dpp v158, v50 row_ror:8 row_mask:0xf bank_mask:0xf
	v_mov_b32_dpp v159, v51 row_ror:8 row_mask:0xf bank_mask:0xf
	v_mov_b32_dpp v48, v52 row_ror:8 row_mask:0xf bank_mask:0x3
	v_mov_b32_dpp v49, v53 row_ror:8 row_mask:0xf bank_mask:0x3
	v_mov_b32_dpp v50, v54 row_ror:8 row_mask:0xf bank_mask:0x3
	v_mov_b32_dpp v51, v55 row_ror:8 row_mask:0xf bank_mask:0x3
	v_mov_b32_dpp v52, v156 quad_perm:[0,1,2,3] row_mask:0xf bank_mask:0xc
	v_mov_b32_dpp v53, v157 quad_perm:[0,1,2,3] row_mask:0xf bank_mask:0xc
	v_mov_b32_dpp v54, v158 quad_perm:[0,1,2,3] row_mask:0xf bank_mask:0xc
	v_mov_b32_dpp v55, v159 quad_perm:[0,1,2,3] row_mask:0xf bank_mask:0xc
	s_waitcnt vmcnt(26)
	v_pk_fma_f32 v[52:53], v[52:53], v[120:121], v[180:181]
	v_pk_fma_f32 v[54:55], v[54:55], v[122:123], v[182:183]
	v_pk_fma_f32 v[48:49], v[48:49], v[120:121], v[184:185]
	v_pk_fma_f32 v[50:51], v[50:51], v[122:123], v[186:187]
	s_add_u32 s98, s90, 0x10000
	s_addc_u32 s99, s91, 0
	global_store_dwordx4 v240, v[52:55], s[98:99] offset:512
	global_store_dwordx4 v242, v[48:51], s[98:99] offset:512
	v_mov_b32_dpp v156, v40 row_ror:8 row_mask:0xf bank_mask:0xf
	v_mov_b32_dpp v157, v41 row_ror:8 row_mask:0xf bank_mask:0xf
	v_mov_b32_dpp v158, v42 row_ror:8 row_mask:0xf bank_mask:0xf
	v_mov_b32_dpp v159, v43 row_ror:8 row_mask:0xf bank_mask:0xf
	v_mov_b32_dpp v40, v44 row_ror:8 row_mask:0xf bank_mask:0x3
	v_mov_b32_dpp v41, v45 row_ror:8 row_mask:0xf bank_mask:0x3
	v_mov_b32_dpp v42, v46 row_ror:8 row_mask:0xf bank_mask:0x3
	v_mov_b32_dpp v43, v47 row_ror:8 row_mask:0xf bank_mask:0x3
	v_mov_b32_dpp v44, v156 quad_perm:[0,1,2,3] row_mask:0xf bank_mask:0xc
	v_mov_b32_dpp v45, v157 quad_perm:[0,1,2,3] row_mask:0xf bank_mask:0xc
	v_mov_b32_dpp v46, v158 quad_perm:[0,1,2,3] row_mask:0xf bank_mask:0xc
	v_mov_b32_dpp v47, v159 quad_perm:[0,1,2,3] row_mask:0xf bank_mask:0xc
	s_waitcnt vmcnt(24)
; #define PG8_BAR __builtin_amdgcn_s_barrier()
; template <class Epi, class Sched, bool ALIGN_EPI = false, bool SP2 = false>
; __device__ __forceinline__ void gemm_phase(PG8_LAS unsigned char* lds, const Gemm g, const Sched& S, const Epi& E, const int wid) {
;     ...
;         if (!has_next) break;
; #pragma unroll
;         for (int a = 0; a < 2; ++a)
; #pragma unroll
;             for (int b = 0; b < 2; ++b)
; #pragma unroll
;                 for (int m = 0; m < 4; ++m)
; #pragma unroll
;                     for (int n = 0; n < 2; ++n) acc[a][b][m][n] = (f32x4){0.f, 0.f, 0.f, 0.f};
;         cur = nxt; cA = nA; cB = nB; ++ui;
;         if constexpr (ALIGN_EPI) { if (wr == 1) PG8_BAR; }
;     __device__ __forceinline__ void operator()(const f32x4 (&acc)[2][2][4][2], const pg8::Unit& u, int wr, int wc, int fr, int fq) const {
;     ...
;         for (int bj = 0; bj < 2; ++bj) {
;             const int col = u.pn * 256 + bj * 128 + wc * 32 + 8 * fq;
;             const f32x4 g0 = *(const f32x4*)(gp + col) * coef, g1 = *(const f32x4*)(gp + col + 4) * coef;
; #pragma unroll
;             for (int ai = 0; ai < 2; ++ai)
; #pragma unroll
;                 for (int m = 0; m < 4; ++m) {
;                     const size_t off = (size_t)(row0 + ai * 128 + m * 16) * DM + col;
;                     const f32x4 x0 = *(const f32x4*)(base + off), x1 = *(const f32x4*)(base + off + 4);
;                     *(f32x4*)(out + off) = x0 + g0 * acc[ai][bj][m][0]; *(f32x4*)(out + off + 4) = x1 + g1 * acc[ai][bj][m][1];
;                     if (m & 1) asm volatile("" ::: "memory");
;                 }
;         }
	v_pk_fma_f32 v[44:45], v[44:45], v[120:121], v[188:189]
	v_pk_fma_f32 v[46:47], v[46:47], v[122:123], v[190:191]
	v_pk_fma_f32 v[40:41], v[40:41], v[120:121], v[192:193]
	v_pk_fma_f32 v[42:43], v[42:43], v[122:123], v[194:195]
	s_add_u32 s98, s90, 0x20000
	s_addc_u32 s99, s91, 0
	global_store_dwordx4 v240, v[44:47], s[98:99] offset:512
	global_store_dwordx4 v242, v[40:43], s[98:99] offset:512
	v_mov_b32_dpp v156, v32 row_ror:8 row_mask:0xf bank_mask:0xf
	v_mov_b32_dpp v157, v33 row_ror:8 row_mask:0xf bank_mask:0xf
	v_mov_b32_dpp v158, v34 row_ror:8 row_mask:0xf bank_mask:0xf
	v_mov_b32_dpp v159, v35 row_ror:8 row_mask:0xf bank_mask:0xf
	v_mov_b32_dpp v32, v36 row_ror:8 row_mask:0xf bank_mask:0x3
	v_mov_b32_dpp v33, v37 row_ror:8 row_mask:0xf bank_mask:0x3
	v_mov_b32_dpp v34, v38 row_ror:8 row_mask:0xf bank_mask:0x3
	v_mov_b32_dpp v35, v39 row_ror:8 row_mask:0xf bank_mask:0x3
	v_mov_b32_dpp v36, v156 quad_perm:[0,1,2,3] row_mask:0xf bank_mask:0xc
	v_mov_b32_dpp v37, v157 quad_perm:[0,1,2,3] row_mask:0xf bank_mask:0xc
	v_mov_b32_dpp v38, v158 quad_perm:[0,1,2,3] row_mask:0xf bank_mask:0xc
	v_mov_b32_dpp v39, v159 quad_perm:[0,1,2,3] row_mask:0xf bank_mask:0xc
	s_waitcnt vmcnt(22)
	v_pk_fma_f32 v[36:37], v[36:37], v[120:121], v[196:197]
	v_pk_fma_f32 v[38:39], v[38:39], v[122:123], v[198:199]
	v_pk_fma_f32 v[32:33], v[32:33], v[120:121], v[200:201]
	v_pk_fma_f32 v[34:35], v[34:35], v[122:123], v[202:203]
	s_add_u32 s98, s90, 0x30000
	s_addc_u32 s99, s91, 0
	global_store_dwordx4 v240, v[36:39], s[98:99] offset:512
	global_store_dwordx4 v242, v[32:35], s[98:99] offset:512
	v_mov_b32_dpp v156, v24 row_ror:8 row_mask:0xf bank_mask:0xf
	v_mov_b32_dpp v157, v25 row_ror:8 row_mask:0xf bank_mask:0xf
	v_mov_b32_dpp v158, v26 row_ror:8 row_mask:0xf bank_mask:0xf
	v_mov_b32_dpp v159, v27 row_ror:8 row_mask:0xf bank_mask:0xf
	v_mov_b32_dpp v24, v28 row_ror:8 row_mask:0xf bank_mask:0x3
	v_mov_b32_dpp v25, v29 row_ror:8 row_mask:0xf bank_mask:0x3
	v_mov_b32_dpp v26, v30 row_ror:8 row_mask:0xf bank_mask:0x3
	v_mov_b32_dpp v27, v31 row_ror:8 row_mask:0xf bank_mask:0x3
	v_mov_b32_dpp v28, v156 quad_perm:[0,1,2,3] row_mask:0xf bank_mask:0xc
	v_mov_b32_dpp v29, v157 quad_perm:[0,1,2,3] row_mask:0xf bank_mask:0xc
	v_mov_b32_dpp v30, v158 quad_perm:[0,1,2,3] row_mask:0xf bank_mask:0xc
	v_mov_b32_dpp v31, v159 quad_perm:[0,1,2,3] row_mask:0xf bank_mask:0xc
	s_waitcnt vmcnt(20)
	v_pk_fma_f32 v[28:29], v[28:29], v[120:121], v[208:209]
	v_pk_fma_f32 v[30:31], v[30:31], v[122:123], v[210:211]
	v_pk_fma_f32 v[24:25], v[24:25], v[120:121], v[212:213]
	v_pk_fma_f32 v[26:27], v[26:27], v[122:123], v[214:215]
	s_add_u32 s98, s90, 0x80000
	s_addc_u32 s99, s91, 0
	global_store_dwordx4 v240, v[28:31], s[98:99] offset:512
	global_store_dwordx4 v242, v[24:27], s[98:99] offset:512
	v_mov_b32_dpp v156, v16 row_ror:8 row_mask:0xf bank_mask:0xf
	v_mov_b32_dpp v157, v17 row_ror:8 row_mask:0xf bank_mask:0xf
	v_mov_b32_dpp v158, v18 row_ror:8 row_mask:0xf bank_mask:0xf
	v_mov_b32_dpp v159, v19 row_ror:8 row_mask:0xf bank_mask:0xf
	v_mov_b32_dpp v16, v20 row_ror:8 row_mask:0xf bank_mask:0x3
	v_mov_b32_dpp v17, v21 row_ror:8 row_mask:0xf bank_mask:0x3
	v_mov_b32_dpp v18, v22 row_ror:8 row_mask:0xf bank_mask:0x3
	v_mov_b32_dpp v19, v23 row_ror:8 row_mask:0xf bank_mask:0x3
	v_mov_b32_dpp v20, v156 quad_perm:[0,1,2,3] row_mask:0xf bank_mask:0xc
	v_mov_b32_dpp v21, v157 quad_perm:[0,1,2,3] row_mask:0xf bank_mask:0xc
	v_mov_b32_dpp v22, v158 quad_perm:[0,1,2,3] row_mask:0xf bank_mask:0xc
	v_mov_b32_dpp v23, v159 quad_perm:[0,1,2,3] row_mask:0xf bank_mask:0xc
	s_waitcnt vmcnt(18)
	v_pk_fma_f32 v[20:21], v[20:21], v[120:121], v[216:217]
	v_pk_fma_f32 v[22:23], v[22:23], v[122:123], v[218:219]
	v_pk_fma_f32 v[16:17], v[16:17], v[120:121], v[220:221]
	v_pk_fma_f32 v[18:19], v[18:19], v[122:123], v[222:223]
	s_add_u32 s98, s90, 0x90000
	s_addc_u32 s99, s91, 0
	global_store_dwordx4 v240, v[20:23], s[98:99] offset:512
	global_store_dwordx4 v242, v[16:19], s[98:99] offset:512
	v_mov_b32_dpp v156, v8 row_ror:8 row_mask:0xf bank_mask:0xf
	v_mov_b32_dpp v157, v9 row_ror:8 row_mask:0xf bank_mask:0xf
	v_mov_b32_dpp v158, v10 row_ror:8 row_mask:0xf bank_mask:0xf
	v_mov_b32_dpp v159, v11 row_ror:8 row_mask:0xf bank_mask:0xf
	v_mov_b32_dpp v8, v12 row_ror:8 row_mask:0xf bank_mask:0x3
	v_mov_b32_dpp v9, v13 row_ror:8 row_mask:0xf bank_mask:0x3
	v_mov_b32_dpp v10, v14 row_ror:8 row_mask:0xf bank_mask:0x3
	v_mov_b32_dpp v11, v15 row_ror:8 row_mask:0xf bank_mask:0x3
	v_mov_b32_dpp v12, v156 quad_perm:[0,1,2,3] row_mask:0xf bank_mask:0xc
	v_mov_b32_dpp v13, v157 quad_perm:[0,1,2,3] row_mask:0xf bank_mask:0xc
	v_mov_b32_dpp v14, v158 quad_perm:[0,1,2,3] row_mask:0xf bank_mask:0xc
	v_mov_b32_dpp v15, v159 quad_perm:[0,1,2,3] row_mask:0xf bank_mask:0xc
	s_waitcnt vmcnt(16)
	v_pk_fma_f32 v[12:13], v[12:13], v[120:121], v[224:225]
	v_pk_fma_f32 v[14:15], v[14:15], v[122:123], v[226:227]
	v_pk_fma_f32 v[8:9], v[8:9], v[120:121], v[228:229]
	v_pk_fma_f32 v[10:11], v[10:11], v[122:123], v[230:231]
	s_add_u32 s98, s90, 0xa0000
	s_addc_u32 s99, s91, 0
	global_store_dwordx4 v240, v[12:15], s[98:99] offset:512
	global_store_dwordx4 v242, v[8:11], s[98:99] offset:512
	v_mov_b32_dpp v156, v0 row_ror:8 row_mask:0xf bank_mask:0xf
	v_mov_b32_dpp v157, v1 row_ror:8 row_mask:0xf bank_mask:0xf
	v_mov_b32_dpp v158, v2 row_ror:8 row_mask:0xf bank_mask:0xf
	v_mov_b32_dpp v159, v3 row_ror:8 row_mask:0xf bank_mask:0xf
	v_mov_b32_dpp v0, v4 row_ror:8 row_mask:0xf bank_mask:0x3
	v_mov_b32_dpp v1, v5 row_ror:8 row_mask:0xf bank_mask:0x3
	v_mov_b32_dpp v2, v6 row_ror:8 row_mask:0xf bank_mask:0x3
	v_mov_b32_dpp v3, v7 row_ror:8 row_mask:0xf bank_mask:0x3
	v_mov_b32_dpp v4, v156 quad_perm:[0,1,2,3] row_mask:0xf bank_mask:0xc
	v_mov_b32_dpp v5, v157 quad_perm:[0,1,2,3] row_mask:0xf bank_mask:0xc
	v_mov_b32_dpp v6, v158 quad_perm:[0,1,2,3] row_mask:0xf bank_mask:0xc
	v_mov_b32_dpp v7, v159 quad_perm:[0,1,2,3] row_mask:0xf bank_mask:0xc
	s_waitcnt vmcnt(14)
	v_pk_fma_f32 v[4:5], v[4:5], v[120:121], v[232:233]
	v_pk_fma_f32 v[6:7], v[6:7], v[122:123], v[234:235]
	v_pk_fma_f32 v[0:1], v[0:1], v[120:121], v[236:237]
	v_pk_fma_f32 v[2:3], v[2:3], v[122:123], v[238:239]
	s_add_u32 s98, s90, 0xb0000
	s_addc_u32 s99, s91, 0
	global_store_dwordx4 v240, v[4:7], s[98:99] offset:512
	global_store_dwordx4 v242, v[0:3], s[98:99] offset:512
	s_andn2_b64 vcc, exec, s[6:7]
	s_mov_b64 s[6:7], -1
	s_cbranch_vccnz .LBB0_1162
	s_andn2_b64 vcc, exec, s[0:1]
	s_cbranch_vccnz .LBB0_1161
	s_barrier
	s_branch .LBB0_1161

;     __device__ __forceinline__ void operator()(const f32x4 (&acc)[2][2][4][2], const pg8::Unit& u, int wr, int wc, int fr, int fq) const {
;         const int row0 = u.pm * 256 + wr * 64 + fr; const float* gp = gate + (size_t)(u.pm >> 5) * NMOD;
; #pragma unroll
;         for (int bj = 0; bj < 2; ++bj) {
;             const int col = u.pn * 256 + bj * 128 + wc * 32 + 8 * fq;
;             const f32x4 g0 = *(const f32x4*)(gp + col) * coef, g1 = *(const f32x4*)(gp + col + 4) * coef;
; #pragma unroll
;             for (int ai = 0; ai < 2; ++ai)
; #pragma unroll
;                 for (int m = 0; m < 4; ++m) {
;                     const size_t off = (size_t)(row0 + ai * 128 + m * 16) * DM + col;
;                     const f32x4 x0 = *(const f32x4*)(base + off), x1 = *(const f32x4*)(base + off + 4);
;                     *(f32x4*)(out + off) = x0 + g0 * acc[ai][bj][m][0]; *(f32x4*)(out + off + 4) = x1 + g1 * acc[ai][bj][m][1];
.LBB0_1396:
	v_and_b32_e32 v243, 8, v156
	v_sub_u32_e32 v240, v156, v243
	v_lshrrev_b32_e32 v243, 1, v243
	v_add_u32_e32 v241, v158, v243
	v_lshl_add_u32 v240, s47, 8, v240
	v_lshl_add_u32 v241, s48, 8, v241
	v_lshlrev_b32_e32 v240, 10, v240
	v_add_lshl_u32 v240, v240, v241, 2
	v_lshlrev_b32_e32 v241, 2, v241
	v_add_u32_e32 v242, 0x8000, v240
	s_ashr_i32 s98, s47, 5
	s_mul_i32 s98, s98, 0x9000
	s_add_u32 s98, s38, s98
	s_addc_u32 s99, s39, 0
	global_load_dwordx4 v[144:147], v241, s[98:99]
	s_add_u32 s100, s90, 0x0
	s_addc_u32 s101, s91, 0
	global_load_dwordx4 v[172:175], v240, s[100:101] nt
	global_load_dwordx4 v[176:179], v242, s[100:101] nt
	s_add_u32 s100, s90, 0x10000
	s_addc_u32 s101, s91, 0
	global_load_dwordx4 v[180:183], v240, s[100:101] nt
	global_load_dwordx4 v[184:187], v242, s[100:101] nt
	s_add_u32 s100, s90, 0x20000
	s_addc_u32 s101, s91, 0
	global_load_dwordx4 v[188:191], v240, s[100:101] nt
	global_load_dwordx4 v[192:195], v242, s[100:101] nt
	s_add_u32 s100, s90, 0x30000
	s_addc_u32 s101, s91, 0
	global_load_dwordx4 v[196:199], v240, s[100:101] nt
	global_load_dwordx4 v[200:203], v242, s[100:101] nt
	s_add_u32 s100, s90, 0x80000
	s_addc_u32 s101, s91, 0
	global_load_dwordx4 v[208:211], v240, s[100:101] nt
	global_load_dwordx4 v[212:215], v242, s[100:101] nt
	s_add_u32 s100, s90, 0x90000
	s_addc_u32 s101, s91, 0
	global_load_dwordx4 v[216:219], v240, s[100:101] nt
	global_load_dwordx4 v[220:223], v242, s[100:101] nt
	s_add_u32 s100, s90, 0xa0000
	s_addc_u32 s101, s91, 0
	global_load_dwordx4 v[224:227], v240, s[100:101] nt
	global_load_dwordx4 v[228:231], v242, s[100:101] nt
	s_add_u32 s100, s90, 0xb0000
	s_addc_u32 s101, s91, 0
	global_load_dwordx4 v[232:235], v240, s[100:101] nt
	global_load_dwordx4 v[236:239], v242, s[100:101] nt
	v_mov_b32_dpp v148, v120 row_ror:8 row_mask:0xf bank_mask:0xf
	v_mov_b32_dpp v149, v121 row_ror:8 row_mask:0xf bank_mask:0xf
	v_mov_b32_dpp v150, v122 row_ror:8 row_mask:0xf bank_mask:0xf
	v_mov_b32_dpp v151, v123 row_ror:8 row_mask:0xf bank_mask:0xf
	v_mov_b32_dpp v120, v124 row_ror:8 row_mask:0xf bank_mask:0x3
	v_mov_b32_dpp v121, v125 row_ror:8 row_mask:0xf bank_mask:0x3
	v_mov_b32_dpp v122, v126 row_ror:8 row_mask:0xf bank_mask:0x3
	v_mov_b32_dpp v123, v127 row_ror:8 row_mask:0xf bank_mask:0x3
	v_mov_b32_dpp v124, v148 quad_perm:[0,1,2,3] row_mask:0xf bank_mask:0xc
	v_mov_b32_dpp v125, v149 quad_perm:[0,1,2,3] row_mask:0xf bank_mask:0xc
	v_mov_b32_dpp v126, v150 quad_perm:[0,1,2,3] row_mask:0xf bank_mask:0xc
	v_mov_b32_dpp v127, v151 quad_perm:[0,1,2,3] row_mask:0xf bank_mask:0xc
	s_waitcnt vmcnt(16)
	v_pk_mul_f32 v[144:145], v[144:145], 0.5 op_sel_hi:[1,0]
	v_pk_mul_f32 v[146:147], v[146:147], 0.5 op_sel_hi:[1,0]
	s_waitcnt vmcnt(14)
	v_pk_fma_f32 v[124:125], v[124:125], v[144:145], v[172:173]
	v_pk_fma_f32 v[126:127], v[126:127], v[146:147], v[174:175]
	v_pk_fma_f32 v[120:121], v[120:121], v[144:145], v[176:177]
	v_pk_fma_f32 v[122:123], v[122:123], v[146:147], v[178:179]
	s_add_u32 s98, s90, 0x0
	s_addc_u32 s99, s91, 0
	global_store_dwordx4 v240, v[124:127], s[98:99]
	global_store_dwordx4 v242, v[120:123], s[98:99]
	s_add_u32 s100, s90, 0x0
	s_addc_u32 s101, s91, 0
	global_load_dwordx4 v[172:175], v240, s[100:101] offset:512 nt
	global_load_dwordx4 v[176:179], v242, s[100:101] offset:512 nt
	s_ashr_i32 s98, s47, 5
	s_mul_i32 s98, s98, 0x9000
	s_add_u32 s98, s38, s98
	s_addc_u32 s99, s39, 0
	global_load_dwordx4 v[120:123], v241, s[98:99] offset:512
	v_mov_b32_dpp v148, v112 row_ror:8 row_mask:0xf bank_mask:0xf
	v_mov_b32_dpp v149, v113 row_ror:8 row_mask:0xf bank_mask:0xf
	v_mov_b32_dpp v150, v114 row_ror:8 row_mask:0xf bank_mask:0xf
	v_mov_b32_dpp v151, v115 row_ror:8 row_mask:0xf bank_mask:0xf
	v_mov_b32_dpp v112, v116 row_ror:8 row_mask:0xf bank_mask:0x3
	v_mov_b32_dpp v113, v117 row_ror:8 row_mask:0xf bank_mask:0x3
	v_mov_b32_dpp v114, v118 row_ror:8 row_mask:0xf bank_mask:0x3
	v_mov_b32_dpp v115, v119 row_ror:8 row_mask:0xf bank_mask:0x3
	v_mov_b32_dpp v116, v148 quad_perm:[0,1,2,3] row_mask:0xf bank_mask:0xc
	v_mov_b32_dpp v117, v149 quad_perm:[0,1,2,3] row_mask:0xf bank_mask:0xc
	v_mov_b32_dpp v118, v150 quad_perm:[0,1,2,3] row_mask:0xf bank_mask:0xc
	v_mov_b32_dpp v119, v151 quad_perm:[0,1,2,3] row_mask:0xf bank_mask:0xc
	s_waitcnt vmcnt(17)
	v_pk_fma_f32 v[116:117], v[116:117], v[144:145], v[180:181]
	v_pk_fma_f32 v[118:119], v[118:119], v[146:147], v[182:183]
	v_pk_fma_f32 v[112:113], v[112:113], v[144:145], v[184:185]
	v_pk_fma_f32 v[114:115], v[114:115], v[146:147], v[186:187]
	s_add_u32 s98, s90, 0x10000
	s_addc_u32 s99, s91, 0
	global_store_dwordx4 v240, v[116:119], s[98:99]
	global_store_dwordx4 v242, v[112:115], s[98:99]
	s_add_u32 s100, s90, 0x10000
	s_addc_u32 s101, s91, 0
	global_load_dwordx4 v[180:183], v240, s[100:101] offset:512 nt
	global_load_dwordx4 v[184:187], v242, s[100:101] offset:512 nt
	v_mov_b32_dpp v148, v104 row_ror:8 row_mask:0xf bank_mask:0xf
	v_mov_b32_dpp v149, v105 row_ror:8 row_mask:0xf bank_mask:0xf
	v_mov_b32_dpp v150, v106 row_ror:8 row_mask:0xf bank_mask:0xf
	v_mov_b32_dpp v151, v107 row_ror:8 row_mask:0xf bank_mask:0xf
	v_mov_b32_dpp v104, v108 row_ror:8 row_mask:0xf bank_mask:0x3
	v_mov_b32_dpp v105, v109 row_ror:8 row_mask:0xf bank_mask:0x3
	v_mov_b32_dpp v106, v110 row_ror:8 row_mask:0xf bank_mask:0x3
	v_mov_b32_dpp v107, v111 row_ror:8 row_mask:0xf bank_mask:0x3
	v_mov_b32_dpp v108, v148 quad_perm:[0,1,2,3] row_mask:0xf bank_mask:0xc
	v_mov_b32_dpp v109, v149 quad_perm:[0,1,2,3] row_mask:0xf bank_mask:0xc
	v_mov_b32_dpp v110, v150 quad_perm:[0,1,2,3] row_mask:0xf bank_mask:0xc
	v_mov_b32_dpp v111, v151 quad_perm:[0,1,2,3] row_mask:0xf bank_mask:0xc
	s_waitcnt vmcnt(19)
;     __device__ __forceinline__ void operator()(const f32x4 (&acc)[2][2][4][2], const pg8::Unit& u, int wr, int wc, int fr, int fq) const {
;     ...
;         for (int bj = 0; bj < 2; ++bj) {
;             const int col = u.pn * 256 + bj * 128 + wc * 32 + 8 * fq;
;             const f32x4 g0 = *(const f32x4*)(gp + col) * coef, g1 = *(const f32x4*)(gp + col + 4) * coef;
; #pragma unroll
;             for (int ai = 0; ai < 2; ++ai)
; #pragma unroll
;                 for (int m = 0; m < 4; ++m) {
;                     const size_t off = (size_t)(row0 + ai * 128 + m * 16) * DM + col;
;                     const f32x4 x0 = *(const f32x4*)(base + off), x1 = *(const f32x4*)(base + off + 4);
;                     *(f32x4*)(out + off) = x0 + g0 * acc[ai][bj][m][0]; *(f32x4*)(out + off + 4) = x1 + g1 * acc[ai][bj][m][1];
;                     if (m & 1) asm volatile("" ::: "memory");
;                 }
	v_pk_fma_f32 v[108:109], v[108:109], v[144:145], v[188:189]
	v_pk_fma_f32 v[110:111], v[110:111], v[146:147], v[190:191]
	v_pk_fma_f32 v[104:105], v[104:105], v[144:145], v[192:193]
	v_pk_fma_f32 v[106:107], v[106:107], v[146:147], v[194:195]
	s_add_u32 s98, s90, 0x20000
	s_addc_u32 s99, s91, 0
	global_store_dwordx4 v240, v[108:111], s[98:99]
	global_store_dwordx4 v242, v[104:107], s[98:99]
	s_add_u32 s100, s90, 0x20000
	s_addc_u32 s101, s91, 0
	global_load_dwordx4 v[188:191], v240, s[100:101] offset:512 nt
	global_load_dwordx4 v[192:195], v242, s[100:101] offset:512 nt
	v_mov_b32_dpp v148, v96 row_ror:8 row_mask:0xf bank_mask:0xf
	v_mov_b32_dpp v149, v97 row_ror:8 row_mask:0xf bank_mask:0xf
	v_mov_b32_dpp v150, v98 row_ror:8 row_mask:0xf bank_mask:0xf
	v_mov_b32_dpp v151, v99 row_ror:8 row_mask:0xf bank_mask:0xf
	v_mov_b32_dpp v96, v100 row_ror:8 row_mask:0xf bank_mask:0x3
	v_mov_b32_dpp v97, v101 row_ror:8 row_mask:0xf bank_mask:0x3
	v_mov_b32_dpp v98, v102 row_ror:8 row_mask:0xf bank_mask:0x3
	v_mov_b32_dpp v99, v103 row_ror:8 row_mask:0xf bank_mask:0x3
	v_mov_b32_dpp v100, v148 quad_perm:[0,1,2,3] row_mask:0xf bank_mask:0xc
	v_mov_b32_dpp v101, v149 quad_perm:[0,1,2,3] row_mask:0xf bank_mask:0xc
	v_mov_b32_dpp v102, v150 quad_perm:[0,1,2,3] row_mask:0xf bank_mask:0xc
	v_mov_b32_dpp v103, v151 quad_perm:[0,1,2,3] row_mask:0xf bank_mask:0xc
	s_waitcnt vmcnt(21)
	v_pk_fma_f32 v[100:101], v[100:101], v[144:145], v[196:197]
	v_pk_fma_f32 v[102:103], v[102:103], v[146:147], v[198:199]
	v_pk_fma_f32 v[96:97], v[96:97], v[144:145], v[200:201]
	v_pk_fma_f32 v[98:99], v[98:99], v[146:147], v[202:203]
	s_add_u32 s98, s90, 0x30000
	s_addc_u32 s99, s91, 0
	global_store_dwordx4 v240, v[100:103], s[98:99]
	global_store_dwordx4 v242, v[96:99], s[98:99]
	s_add_u32 s100, s90, 0x30000
	s_addc_u32 s101, s91, 0
	global_load_dwordx4 v[196:199], v240, s[100:101] offset:512 nt
	global_load_dwordx4 v[200:203], v242, s[100:101] offset:512 nt
	v_mov_b32_dpp v148, v88 row_ror:8 row_mask:0xf bank_mask:0xf
	v_mov_b32_dpp v149, v89 row_ror:8 row_mask:0xf bank_mask:0xf
	v_mov_b32_dpp v150, v90 row_ror:8 row_mask:0xf bank_mask:0xf
	v_mov_b32_dpp v151, v91 row_ror:8 row_mask:0xf bank_mask:0xf
	v_mov_b32_dpp v88, v92 row_ror:8 row_mask:0xf bank_mask:0x3
	v_mov_b32_dpp v89, v93 row_ror:8 row_mask:0xf bank_mask:0x3
	v_mov_b32_dpp v90, v94 row_ror:8 row_mask:0xf bank_mask:0x3
	v_mov_b32_dpp v91, v95 row_ror:8 row_mask:0xf bank_mask:0x3
	v_mov_b32_dpp v92, v148 quad_perm:[0,1,2,3] row_mask:0xf bank_mask:0xc
	v_mov_b32_dpp v93, v149 quad_perm:[0,1,2,3] row_mask:0xf bank_mask:0xc
	v_mov_b32_dpp v94, v150 quad_perm:[0,1,2,3] row_mask:0xf bank_mask:0xc
	v_mov_b32_dpp v95, v151 quad_perm:[0,1,2,3] row_mask:0xf bank_mask:0xc
	s_waitcnt vmcnt(23)
	v_pk_fma_f32 v[92:93], v[92:93], v[144:145], v[208:209]
	v_pk_fma_f32 v[94:95], v[94:95], v[146:147], v[210:211]
	v_pk_fma_f32 v[88:89], v[88:89], v[144:145], v[212:213]
	v_pk_fma_f32 v[90:91], v[90:91], v[146:147], v[214:215]
	s_add_u32 s98, s90, 0x80000
	s_addc_u32 s99, s91, 0
	global_store_dwordx4 v240, v[92:95], s[98:99]
	global_store_dwordx4 v242, v[88:91], s[98:99]
	s_add_u32 s100, s90, 0x80000
	s_addc_u32 s101, s91, 0
	global_load_dwordx4 v[208:211], v240, s[100:101] offset:512 nt
	global_load_dwordx4 v[212:215], v242, s[100:101] offset:512 nt
	v_mov_b32_dpp v148, v80 row_ror:8 row_mask:0xf bank_mask:0xf
	v_mov_b32_dpp v149, v81 row_ror:8 row_mask:0xf bank_mask:0xf
	v_mov_b32_dpp v150, v82 row_ror:8 row_mask:0xf bank_mask:0xf
	v_mov_b32_dpp v151, v83 row_ror:8 row_mask:0xf bank_mask:0xf
	v_mov_b32_dpp v80, v84 row_ror:8 row_mask:0xf bank_mask:0x3
	v_mov_b32_dpp v81, v85 row_ror:8 row_mask:0xf bank_mask:0x3
	v_mov_b32_dpp v82, v86 row_ror:8 row_mask:0xf bank_mask:0x3
	v_mov_b32_dpp v83, v87 row_ror:8 row_mask:0xf bank_mask:0x3
	v_mov_b32_dpp v84, v148 quad_perm:[0,1,2,3] row_mask:0xf bank_mask:0xc
	v_mov_b32_dpp v85, v149 quad_perm:[0,1,2,3] row_mask:0xf bank_mask:0xc
	v_mov_b32_dpp v86, v150 quad_perm:[0,1,2,3] row_mask:0xf bank_mask:0xc
	v_mov_b32_dpp v87, v151 quad_perm:[0,1,2,3] row_mask:0xf bank_mask:0xc
	s_waitcnt vmcnt(25)
	v_pk_fma_f32 v[84:85], v[84:85], v[144:145], v[216:217]
	v_pk_fma_f32 v[86:87], v[86:87], v[146:147], v[218:219]
	v_pk_fma_f32 v[80:81], v[80:81], v[144:145], v[220:221]
	v_pk_fma_f32 v[82:83], v[82:83], v[146:147], v[222:223]
	s_add_u32 s98, s90, 0x90000
	s_addc_u32 s99, s91, 0
	global_store_dwordx4 v240, v[84:87], s[98:99]
	global_store_dwordx4 v242, v[80:83], s[98:99]
	s_add_u32 s100, s90, 0x90000
	s_addc_u32 s101, s91, 0
	global_load_dwordx4 v[216:219], v240, s[100:101] offset:512 nt
	global_load_dwordx4 v[220:223], v242, s[100:101] offset:512 nt
	v_mov_b32_dpp v148, v72 row_ror:8 row_mask:0xf bank_mask:0xf
	v_mov_b32_dpp v149, v73 row_ror:8 row_mask:0xf bank_mask:0xf
	v_mov_b32_dpp v150, v74 row_ror:8 row_mask:0xf bank_mask:0xf
	v_mov_b32_dpp v151, v75 row_ror:8 row_mask:0xf bank_mask:0xf
	v_mov_b32_dpp v72, v76 row_ror:8 row_mask:0xf bank_mask:0x3
	v_mov_b32_dpp v73, v77 row_ror:8 row_mask:0xf bank_mask:0x3
	v_mov_b32_dpp v74, v78 row_ror:8 row_mask:0xf bank_mask:0x3
	v_mov_b32_dpp v75, v79 row_ror:8 row_mask:0xf bank_mask:0x3
	v_mov_b32_dpp v76, v148 quad_perm:[0,1,2,3] row_mask:0xf bank_mask:0xc
	v_mov_b32_dpp v77, v149 quad_perm:[0,1,2,3] row_mask:0xf bank_mask:0xc
	v_mov_b32_dpp v78, v150 quad_perm:[0,1,2,3] row_mask:0xf bank_mask:0xc
	v_mov_b32_dpp v79, v151 quad_perm:[0,1,2,3] row_mask:0xf bank_mask:0xc
	s_waitcnt vmcnt(27)
;     __device__ __forceinline__ void operator()(const f32x4 (&acc)[2][2][4][2], const pg8::Unit& u, int wr, int wc, int fr, int fq) const {
;     ...
;         for (int bj = 0; bj < 2; ++bj) {
;             const int col = u.pn * 256 + bj * 128 + wc * 32 + 8 * fq;
;             const f32x4 g0 = *(const f32x4*)(gp + col) * coef, g1 = *(const f32x4*)(gp + col + 4) * coef;
; #pragma unroll
;             for (int ai = 0; ai < 2; ++ai)
; #pragma unroll
;                 for (int m = 0; m < 4; ++m) {
;                     const size_t off = (size_t)(row0 + ai * 128 + m * 16) * DM + col;
;                     const f32x4 x0 = *(const f32x4*)(base + off), x1 = *(const f32x4*)(base + off + 4);
;                     *(f32x4*)(out + off) = x0 + g0 * acc[ai][bj][m][0]; *(f32x4*)(out + off + 4) = x1 + g1 * acc[ai][bj][m][1];
;                     if (m & 1) asm volatile("" ::: "memory");
;                 }
	v_pk_fma_f32 v[76:77], v[76:77], v[144:145], v[224:225]
	v_pk_fma_f32 v[78:79], v[78:79], v[146:147], v[226:227]
	v_pk_fma_f32 v[72:73], v[72:73], v[144:145], v[228:229]
	v_pk_fma_f32 v[74:75], v[74:75], v[146:147], v[230:231]
	s_add_u32 s98, s90, 0xa0000
	s_addc_u32 s99, s91, 0
	global_store_dwordx4 v240, v[76:79], s[98:99]
	global_store_dwordx4 v242, v[72:75], s[98:99]
	s_add_u32 s100, s90, 0xa0000
	s_addc_u32 s101, s91, 0
	global_load_dwordx4 v[224:227], v240, s[100:101] offset:512 nt
	global_load_dwordx4 v[228:231], v242, s[100:101] offset:512 nt
	v_mov_b32_dpp v148, v64 row_ror:8 row_mask:0xf bank_mask:0xf
	v_mov_b32_dpp v149, v65 row_ror:8 row_mask:0xf bank_mask:0xf
	v_mov_b32_dpp v150, v66 row_ror:8 row_mask:0xf bank_mask:0xf
	v_mov_b32_dpp v151, v67 row_ror:8 row_mask:0xf bank_mask:0xf
	v_mov_b32_dpp v64, v68 row_ror:8 row_mask:0xf bank_mask:0x3
	v_mov_b32_dpp v65, v69 row_ror:8 row_mask:0xf bank_mask:0x3
	v_mov_b32_dpp v66, v70 row_ror:8 row_mask:0xf bank_mask:0x3
	v_mov_b32_dpp v67, v71 row_ror:8 row_mask:0xf bank_mask:0x3
	v_mov_b32_dpp v68, v148 quad_perm:[0,1,2,3] row_mask:0xf bank_mask:0xc
	v_mov_b32_dpp v69, v149 quad_perm:[0,1,2,3] row_mask:0xf bank_mask:0xc
	v_mov_b32_dpp v70, v150 quad_perm:[0,1,2,3] row_mask:0xf bank_mask:0xc
	v_mov_b32_dpp v71, v151 quad_perm:[0,1,2,3] row_mask:0xf bank_mask:0xc
	s_waitcnt vmcnt(29)
	v_pk_fma_f32 v[68:69], v[68:69], v[144:145], v[232:233]
	v_pk_fma_f32 v[70:71], v[70:71], v[146:147], v[234:235]
	v_pk_fma_f32 v[64:65], v[64:65], v[144:145], v[236:237]
	v_pk_fma_f32 v[66:67], v[66:67], v[146:147], v[238:239]
	s_add_u32 s98, s90, 0xb0000
	s_addc_u32 s99, s91, 0
	global_store_dwordx4 v240, v[68:71], s[98:99]
	global_store_dwordx4 v242, v[64:67], s[98:99]
	s_add_u32 s100, s90, 0xb0000
	s_addc_u32 s101, s91, 0
	global_load_dwordx4 v[232:235], v240, s[100:101] offset:512 nt
	global_load_dwordx4 v[236:239], v242, s[100:101] offset:512 nt
	v_mov_b32_dpp v148, v56 row_ror:8 row_mask:0xf bank_mask:0xf
	v_mov_b32_dpp v149, v57 row_ror:8 row_mask:0xf bank_mask:0xf
	v_mov_b32_dpp v150, v58 row_ror:8 row_mask:0xf bank_mask:0xf
	v_mov_b32_dpp v151, v59 row_ror:8 row_mask:0xf bank_mask:0xf
	v_mov_b32_dpp v56, v60 row_ror:8 row_mask:0xf bank_mask:0x3
	v_mov_b32_dpp v57, v61 row_ror:8 row_mask:0xf bank_mask:0x3
	v_mov_b32_dpp v58, v62 row_ror:8 row_mask:0xf bank_mask:0x3
	v_mov_b32_dpp v59, v63 row_ror:8 row_mask:0xf bank_mask:0x3
	v_mov_b32_dpp v60, v148 quad_perm:[0,1,2,3] row_mask:0xf bank_mask:0xc
	v_mov_b32_dpp v61, v149 quad_perm:[0,1,2,3] row_mask:0xf bank_mask:0xc
	v_mov_b32_dpp v62, v150 quad_perm:[0,1,2,3] row_mask:0xf bank_mask:0xc
	v_mov_b32_dpp v63, v151 quad_perm:[0,1,2,3] row_mask:0xf bank_mask:0xc
	s_waitcnt vmcnt(28)
	v_pk_mul_f32 v[120:121], v[120:121], 0.5 op_sel_hi:[1,0]
	v_pk_mul_f32 v[122:123], v[122:123], 0.5 op_sel_hi:[1,0]
	v_pk_fma_f32 v[60:61], v[60:61], v[120:121], v[172:173]
	v_pk_fma_f32 v[62:63], v[62:63], v[122:123], v[174:175]
	v_pk_fma_f32 v[56:57], v[56:57], v[120:121], v[176:177]
	v_pk_fma_f32 v[58:59], v[58:59], v[122:123], v[178:179]
	s_add_u32 s98, s90, 0x0
	s_addc_u32 s99, s91, 0
	global_store_dwordx4 v240, v[60:63], s[98:99] offset:512
	global_store_dwordx4 v242, v[56:59], s[98:99] offset:512
	v_mov_b32_dpp v148, v48 row_ror:8 row_mask:0xf bank_mask:0xf
	v_mov_b32_dpp v149, v49 row_ror:8 row_mask:0xf bank_mask:0xf
	v_mov_b32_dpp v150, v50 row_ror:8 row_mask:0xf bank_mask:0xf
	v_mov_b32_dpp v151, v51 row_ror:8 row_mask:0xf bank_mask:0xf
	v_mov_b32_dpp v48, v52 row_ror:8 row_mask:0xf bank_mask:0x3
	v_mov_b32_dpp v49, v53 row_ror:8 row_mask:0xf bank_mask:0x3
	v_mov_b32_dpp v50, v54 row_ror:8 row_mask:0xf bank_mask:0x3
	v_mov_b32_dpp v51, v55 row_ror:8 row_mask:0xf bank_mask:0x3
	v_mov_b32_dpp v52, v148 quad_perm:[0,1,2,3] row_mask:0xf bank_mask:0xc
	v_mov_b32_dpp v53, v149 quad_perm:[0,1,2,3] row_mask:0xf bank_mask:0xc
	v_mov_b32_dpp v54, v150 quad_perm:[0,1,2,3] row_mask:0xf bank_mask:0xc
	v_mov_b32_dpp v55, v151 quad_perm:[0,1,2,3] row_mask:0xf bank_mask:0xc
	s_waitcnt vmcnt(26)
	v_pk_fma_f32 v[52:53], v[52:53], v[120:121], v[180:181]
	v_pk_fma_f32 v[54:55], v[54:55], v[122:123], v[182:183]
	v_pk_fma_f32 v[48:49], v[48:49], v[120:121], v[184:185]
	v_pk_fma_f32 v[50:51], v[50:51], v[122:123], v[186:187]
	s_add_u32 s98, s90, 0x10000
	s_addc_u32 s99, s91, 0
	global_store_dwordx4 v240, v[52:55], s[98:99] offset:512
	global_store_dwordx4 v242, v[48:51], s[98:99] offset:512
	v_mov_b32_dpp v148, v40 row_ror:8 row_mask:0xf bank_mask:0xf
	v_mov_b32_dpp v149, v41 row_ror:8 row_mask:0xf bank_mask:0xf
	v_mov_b32_dpp v150, v42 row_ror:8 row_mask:0xf bank_mask:0xf
	v_mov_b32_dpp v151, v43 row_ror:8 row_mask:0xf bank_mask:0xf
	v_mov_b32_dpp v40, v44 row_ror:8 row_mask:0xf bank_mask:0x3
	v_mov_b32_dpp v41, v45 row_ror:8 row_mask:0xf bank_mask:0x3
	v_mov_b32_dpp v42, v46 row_ror:8 row_mask:0xf bank_mask:0x3
	v_mov_b32_dpp v43, v47 row_ror:8 row_mask:0xf bank_mask:0x3
	v_mov_b32_dpp v44, v148 quad_perm:[0,1,2,3] row_mask:0xf bank_mask:0xc
	v_mov_b32_dpp v45, v149 quad_perm:[0,1,2,3] row_mask:0xf bank_mask:0xc
	v_mov_b32_dpp v46, v150 quad_perm:[0,1,2,3] row_mask:0xf bank_mask:0xc
	v_mov_b32_dpp v47, v151 quad_perm:[0,1,2,3] row_mask:0xf bank_mask:0xc
	s_waitcnt vmcnt(24)
; #define PG8_BAR __builtin_amdgcn_s_barrier()
; template <class Epi, class Sched, bool ALIGN_EPI = false, bool SP2 = false>
; __device__ __forceinline__ void gemm_phase(PG8_LAS unsigned char* lds, const Gemm g, const Sched& S, const Epi& E, const int wid) {
;     ...
;         if (!has_next) break;
; #pragma unroll
;         for (int a = 0; a < 2; ++a)
; #pragma unroll
;             for (int b = 0; b < 2; ++b)
; #pragma unroll
;                 for (int m = 0; m < 4; ++m)
; #pragma unroll
;                     for (int n = 0; n < 2; ++n) acc[a][b][m][n] = (f32x4){0.f, 0.f, 0.f, 0.f};
;         cur = nxt; cA = nA; cB = nB; ++ui;
;         if constexpr (ALIGN_EPI) { if (wr == 1) PG8_BAR; }
;     __device__ __forceinline__ void operator()(const f32x4 (&acc)[2][2][4][2], const pg8::Unit& u, int wr, int wc, int fr, int fq) const {
;     ...
;         for (int bj = 0; bj < 2; ++bj) {
;             const int col = u.pn * 256 + bj * 128 + wc * 32 + 8 * fq;
;             const f32x4 g0 = *(const f32x4*)(gp + col) * coef, g1 = *(const f32x4*)(gp + col + 4) * coef;
; #pragma unroll
;             for (int ai = 0; ai < 2; ++ai)
; #pragma unroll
;                 for (int m = 0; m < 4; ++m) {
;                     const size_t off = (size_t)(row0 + ai * 128 + m * 16) * DM + col;
;                     const f32x4 x0 = *(const f32x4*)(base + off), x1 = *(const f32x4*)(base + off + 4);
;                     *(f32x4*)(out + off) = x0 + g0 * acc[ai][bj][m][0]; *(f32x4*)(out + off + 4) = x1 + g1 * acc[ai][bj][m][1];
;                     if (m & 1) asm volatile("" ::: "memory");
;                 }
;         }
	v_pk_fma_f32 v[44:45], v[44:45], v[120:121], v[188:189]
	v_pk_fma_f32 v[46:47], v[46:47], v[122:123], v[190:191]
	v_pk_fma_f32 v[40:41], v[40:41], v[120:121], v[192:193]
	v_pk_fma_f32 v[42:43], v[42:43], v[122:123], v[194:195]
	s_add_u32 s98, s90, 0x20000
	s_addc_u32 s99, s91, 0
	global_store_dwordx4 v240, v[44:47], s[98:99] offset:512
	global_store_dwordx4 v242, v[40:43], s[98:99] offset:512
	v_mov_b32_dpp v148, v32 row_ror:8 row_mask:0xf bank_mask:0xf
	v_mov_b32_dpp v149, v33 row_ror:8 row_mask:0xf bank_mask:0xf
	v_mov_b32_dpp v150, v34 row_ror:8 row_mask:0xf bank_mask:0xf
	v_mov_b32_dpp v151, v35 row_ror:8 row_mask:0xf bank_mask:0xf
	v_mov_b32_dpp v32, v36 row_ror:8 row_mask:0xf bank_mask:0x3
	v_mov_b32_dpp v33, v37 row_ror:8 row_mask:0xf bank_mask:0x3
	v_mov_b32_dpp v34, v38 row_ror:8 row_mask:0xf bank_mask:0x3
	v_mov_b32_dpp v35, v39 row_ror:8 row_mask:0xf bank_mask:0x3
	v_mov_b32_dpp v36, v148 quad_perm:[0,1,2,3] row_mask:0xf bank_mask:0xc
	v_mov_b32_dpp v37, v149 quad_perm:[0,1,2,3] row_mask:0xf bank_mask:0xc
	v_mov_b32_dpp v38, v150 quad_perm:[0,1,2,3] row_mask:0xf bank_mask:0xc
	v_mov_b32_dpp v39, v151 quad_perm:[0,1,2,3] row_mask:0xf bank_mask:0xc
	s_waitcnt vmcnt(22)
	v_pk_fma_f32 v[36:37], v[36:37], v[120:121], v[196:197]
	v_pk_fma_f32 v[38:39], v[38:39], v[122:123], v[198:199]
	v_pk_fma_f32 v[32:33], v[32:33], v[120:121], v[200:201]
	v_pk_fma_f32 v[34:35], v[34:35], v[122:123], v[202:203]
	s_add_u32 s98, s90, 0x30000
	s_addc_u32 s99, s91, 0
	global_store_dwordx4 v240, v[36:39], s[98:99] offset:512
	global_store_dwordx4 v242, v[32:35], s[98:99] offset:512
	v_mov_b32_dpp v148, v24 row_ror:8 row_mask:0xf bank_mask:0xf
	v_mov_b32_dpp v149, v25 row_ror:8 row_mask:0xf bank_mask:0xf
	v_mov_b32_dpp v150, v26 row_ror:8 row_mask:0xf bank_mask:0xf
	v_mov_b32_dpp v151, v27 row_ror:8 row_mask:0xf bank_mask:0xf
	v_mov_b32_dpp v24, v28 row_ror:8 row_mask:0xf bank_mask:0x3
	v_mov_b32_dpp v25, v29 row_ror:8 row_mask:0xf bank_mask:0x3
	v_mov_b32_dpp v26, v30 row_ror:8 row_mask:0xf bank_mask:0x3
	v_mov_b32_dpp v27, v31 row_ror:8 row_mask:0xf bank_mask:0x3
	v_mov_b32_dpp v28, v148 quad_perm:[0,1,2,3] row_mask:0xf bank_mask:0xc
	v_mov_b32_dpp v29, v149 quad_perm:[0,1,2,3] row_mask:0xf bank_mask:0xc
	v_mov_b32_dpp v30, v150 quad_perm:[0,1,2,3] row_mask:0xf bank_mask:0xc
	v_mov_b32_dpp v31, v151 quad_perm:[0,1,2,3] row_mask:0xf bank_mask:0xc
	s_waitcnt vmcnt(20)
	v_pk_fma_f32 v[28:29], v[28:29], v[120:121], v[208:209]
	v_pk_fma_f32 v[30:31], v[30:31], v[122:123], v[210:211]
	v_pk_fma_f32 v[24:25], v[24:25], v[120:121], v[212:213]
	v_pk_fma_f32 v[26:27], v[26:27], v[122:123], v[214:215]
	s_add_u32 s98, s90, 0x80000
	s_addc_u32 s99, s91, 0
	global_store_dwordx4 v240, v[28:31], s[98:99] offset:512
	global_store_dwordx4 v242, v[24:27], s[98:99] offset:512
	v_mov_b32_dpp v148, v16 row_ror:8 row_mask:0xf bank_mask:0xf
	v_mov_b32_dpp v149, v17 row_ror:8 row_mask:0xf bank_mask:0xf
	v_mov_b32_dpp v150, v18 row_ror:8 row_mask:0xf bank_mask:0xf
	v_mov_b32_dpp v151, v19 row_ror:8 row_mask:0xf bank_mask:0xf
	v_mov_b32_dpp v16, v20 row_ror:8 row_mask:0xf bank_mask:0x3
	v_mov_b32_dpp v17, v21 row_ror:8 row_mask:0xf bank_mask:0x3
	v_mov_b32_dpp v18, v22 row_ror:8 row_mask:0xf bank_mask:0x3
	v_mov_b32_dpp v19, v23 row_ror:8 row_mask:0xf bank_mask:0x3
	v_mov_b32_dpp v20, v148 quad_perm:[0,1,2,3] row_mask:0xf bank_mask:0xc
	v_mov_b32_dpp v21, v149 quad_perm:[0,1,2,3] row_mask:0xf bank_mask:0xc
	v_mov_b32_dpp v22, v150 quad_perm:[0,1,2,3] row_mask:0xf bank_mask:0xc
	v_mov_b32_dpp v23, v151 quad_perm:[0,1,2,3] row_mask:0xf bank_mask:0xc
	s_waitcnt vmcnt(18)
	v_pk_fma_f32 v[20:21], v[20:21], v[120:121], v[216:217]
	v_pk_fma_f32 v[22:23], v[22:23], v[122:123], v[218:219]
	v_pk_fma_f32 v[16:17], v[16:17], v[120:121], v[220:221]
	v_pk_fma_f32 v[18:19], v[18:19], v[122:123], v[222:223]
	s_add_u32 s98, s90, 0x90000
	s_addc_u32 s99, s91, 0
	global_store_dwordx4 v240, v[20:23], s[98:99] offset:512
	global_store_dwordx4 v242, v[16:19], s[98:99] offset:512
	v_mov_b32_dpp v148, v8 row_ror:8 row_mask:0xf bank_mask:0xf
	v_mov_b32_dpp v149, v9 row_ror:8 row_mask:0xf bank_mask:0xf
	v_mov_b32_dpp v150, v10 row_ror:8 row_mask:0xf bank_mask:0xf
	v_mov_b32_dpp v151, v11 row_ror:8 row_mask:0xf bank_mask:0xf
	v_mov_b32_dpp v8, v12 row_ror:8 row_mask:0xf bank_mask:0x3
	v_mov_b32_dpp v9, v13 row_ror:8 row_mask:0xf bank_mask:0x3
	v_mov_b32_dpp v10, v14 row_ror:8 row_mask:0xf bank_mask:0x3
	v_mov_b32_dpp v11, v15 row_ror:8 row_mask:0xf bank_mask:0x3
	v_mov_b32_dpp v12, v148 quad_perm:[0,1,2,3] row_mask:0xf bank_mask:0xc
	v_mov_b32_dpp v13, v149 quad_perm:[0,1,2,3] row_mask:0xf bank_mask:0xc
	v_mov_b32_dpp v14, v150 quad_perm:[0,1,2,3] row_mask:0xf bank_mask:0xc
	v_mov_b32_dpp v15, v151 quad_perm:[0,1,2,3] row_mask:0xf bank_mask:0xc
	s_waitcnt vmcnt(16)
	v_pk_fma_f32 v[12:13], v[12:13], v[120:121], v[224:225]
	v_pk_fma_f32 v[14:15], v[14:15], v[122:123], v[226:227]
	v_pk_fma_f32 v[8:9], v[8:9], v[120:121], v[228:229]
	v_pk_fma_f32 v[10:11], v[10:11], v[122:123], v[230:231]
	s_add_u32 s98, s90, 0xa0000
	s_addc_u32 s99, s91, 0
	global_store_dwordx4 v240, v[12:15], s[98:99] offset:512
	global_store_dwordx4 v242, v[8:11], s[98:99] offset:512
	v_mov_b32_dpp v148, v0 row_ror:8 row_mask:0xf bank_mask:0xf
	v_mov_b32_dpp v149, v1 row_ror:8 row_mask:0xf bank_mask:0xf
	v_mov_b32_dpp v150, v2 row_ror:8 row_mask:0xf bank_mask:0xf
	v_mov_b32_dpp v151, v3 row_ror:8 row_mask:0xf bank_mask:0xf
	v_mov_b32_dpp v0, v4 row_ror:8 row_mask:0xf bank_mask:0x3
	v_mov_b32_dpp v1, v5 row_ror:8 row_mask:0xf bank_mask:0x3
	v_mov_b32_dpp v2, v6 row_ror:8 row_mask:0xf bank_mask:0x3
	v_mov_b32_dpp v3, v7 row_ror:8 row_mask:0xf bank_mask:0x3
	v_mov_b32_dpp v4, v148 quad_perm:[0,1,2,3] row_mask:0xf bank_mask:0xc
	v_mov_b32_dpp v5, v149 quad_perm:[0,1,2,3] row_mask:0xf bank_mask:0xc
	v_mov_b32_dpp v6, v150 quad_perm:[0,1,2,3] row_mask:0xf bank_mask:0xc
	v_mov_b32_dpp v7, v151 quad_perm:[0,1,2,3] row_mask:0xf bank_mask:0xc
	s_waitcnt vmcnt(14)
	v_pk_fma_f32 v[4:5], v[4:5], v[120:121], v[232:233]
	v_pk_fma_f32 v[6:7], v[6:7], v[122:123], v[234:235]
	v_pk_fma_f32 v[0:1], v[0:1], v[120:121], v[236:237]
	v_pk_fma_f32 v[2:3], v[2:3], v[122:123], v[238:239]
	s_add_u32 s98, s90, 0xb0000
	s_addc_u32 s99, s91, 0
	global_store_dwordx4 v240, v[4:7], s[98:99] offset:512
	global_store_dwordx4 v242, v[0:3], s[98:99] offset:512
	s_and_b64 vcc, exec, s[0:1]
	s_mov_b64 s[0:1], -1
	s_cbranch_vccnz .LBB0_1381
	s_andn2_b64 vcc, exec, s[6:7]
	s_cbranch_vccnz .LBB0_1380
	s_barrier
	s_branch .LBB0_1380
